# de-serialized load chains in gla1/gla3/dil/sb items (loads issued together, consumers fed by moves) on top of K-loop handoff reorder
# speedup vs baseline: 1.0090x; 1.0090x over previous
; __device__ __forceinline__ unsigned pk2(float lo, float hi) { const f32v2_t v = {lo, hi}; return __builtin_bit_cast(unsigned, __builtin_convertvector(v, bf16v2_t)); }
; __device__ __forceinline__ size_t pidx(int row, int col) { return (size_t)(col >> 7) * ((size_t)T * 128) + (size_t)row * 128 + (col & 127); }
; __device__ __forceinline__ float bflo(unsigned u) { return __uint_as_float(u << 16); }
; __device__ __forceinline__ float bfhi(unsigned u) { return __uint_as_float(u & 0xffff0000u); }
; __device__ __forceinline__ float siluf_(float x) { return x * __builtin_amdgcn_rcpf(1.f + __expf(-fmaxf(x, -80.f))); }
; __device__ __forceinline__ void gla3_item(const Params& p, int item, int l, unsigned char* lds) {
;     ...
;     const float rinv = rsqrtf((ssq[iq] + ssq[64 + iq]) * (1.f / 256.f) + EPS);
;     const size_t trow = (size_t)(t0 + iq);
; #pragma unroll
;     for (int ebl = 0; ebl < 8; ++ebl) {
;         const int e = 16 * (8 * eh + ebl) + 4 * fq;
;         const u32x2 rr = *(const u32x2*)(P + pidx((int)trow, C_RG + h * 256 + e));
;         const f32x4 gn = *(const f32x4*)(ogain + e);
;         const float y0 = o[ebl][0] * rinv * gn[0] * siluf_(bflo(rr[0])), y1 = o[ebl][1] * rinv * gn[1] * siluf_(bfhi(rr[0]));
;         const float y2 = o[ebl][2] * rinv * gn[2] * siluf_(bflo(rr[1])), y3 = o[ebl][3] * rinv * gn[3] * siluf_(bfhi(rr[1]));
;         u32x2 ov = {pk2(y0, y1), pk2(y2, y3)};
;         *(u32x2*)(OG + trow * D + h * 256 + e) = ov;
;     }
.LBB0_56:
	s_or_b64 exec, exec, s[4:5]
	v_or_b32_e32 v24, s13, v54
	v_lshlrev_b32_e32 v0, 8, v24
	s_add_i32 s4, s40, 0x1a00
	s_waitcnt lgkmcnt(0)
	v_lshl_add_u64 v[22:23], s[0:1], 0, v[0:1]
	v_lshlrev_b32_e32 v0, 12, v24
	v_lshl_add_u64 v[26:27], s[36:37], 0, v[0:1]
	v_add_u32_e32 v0, s4, v57
	v_ashrrev_i32_e32 v24, 7, v0
	v_ashrrev_i32_e32 v25, 31, v24
	v_lshlrev_b64 v[24:25], 21, v[24:25]
	v_lshl_add_u64 v[28:29], v[22:23], 0, v[24:25]
	v_lshlrev_b32_e32 v0, 1, v55
	v_lshl_add_u64 v[22:23], v[28:29], 0, v[0:1]
	s_barrier
	flat_load_dwordx2 v[32:33], v[22:23]
	v_or_b32_e32 v30, v55, v56
	v_ashrrev_i32_e32 v31, 31, v30
	v_lshl_add_u64 v[24:25], v[30:31], 2, s[2:3]
	global_load_dwordx4 v[46:49], v[24:25], off
	s_movk_i32 s4, 0x1c
	v_bitop3_b32 v0, v30, s4, 16 bitop3:0xc8
	v_lshlrev_b32_e32 v0, 1, v0
	v_lshl_add_u64 v[136:137], v[28:29], 0, v[0:1]
	global_load_dwordx2 v[90:91], v[136:137], off
	global_load_dwordx4 v[108:111], v[24:25], off offset:64
	s_movk_i32 s4, 0x2c
	v_bitop3_b32 v0, v30, s4, 32 bitop3:0xc8
	v_lshlrev_b32_e32 v0, 1, v0
	v_lshl_add_u64 v[136:137], v[28:29], 0, v[0:1]
	global_load_dwordx2 v[92:93], v[136:137], off
	global_load_dwordx4 v[112:115], v[24:25], off offset:128
	s_movk_i32 s4, 0x3c
	v_bitop3_b32 v0, v30, s4, 48 bitop3:0xc8
	v_lshlrev_b32_e32 v0, 1, v0
	v_lshl_add_u64 v[136:137], v[28:29], 0, v[0:1]
	global_load_dwordx2 v[94:95], v[136:137], off
	global_load_dwordx4 v[116:119], v[24:25], off offset:192
	s_movk_i32 s4, 0x4c
	v_bitop3_b32 v0, v30, s4, 64 bitop3:0xc8
	v_lshlrev_b32_e32 v0, 1, v0
	v_lshl_add_u64 v[136:137], v[28:29], 0, v[0:1]
	global_load_dwordx2 v[96:97], v[136:137], off
	global_load_dwordx4 v[120:123], v[24:25], off offset:256
	s_movk_i32 s4, 0x5c
	v_bitop3_b32 v0, v30, s4, v212 bitop3:0xc8
	v_lshlrev_b32_e32 v0, 1, v0
	v_lshl_add_u64 v[136:137], v[28:29], 0, v[0:1]
	global_load_dwordx2 v[98:99], v[136:137], off
	global_load_dwordx4 v[124:127], v[24:25], off offset:320
	s_movk_i32 s4, 0x6c
	v_bitop3_b32 v0, v30, s4, v213 bitop3:0xc8
	v_lshlrev_b32_e32 v0, 1, v0
	v_lshl_add_u64 v[136:137], v[28:29], 0, v[0:1]
	global_load_dwordx2 v[100:101], v[136:137], off
	global_load_dwordx4 v[128:131], v[24:25], off offset:384
	s_movk_i32 s4, 0x7c
	v_bitop3_b32 v0, v30, s4, v214 bitop3:0xc8
	v_lshlrev_b32_e32 v0, 1, v0
	v_lshl_add_u64 v[136:137], v[28:29], 0, v[0:1]
	global_load_dwordx2 v[102:103], v[136:137], off
	global_load_dwordx4 v[132:135], v[24:25], off offset:448
	v_lshl_add_u32 v0, v54, 2, 0
	v_add_u32_e32 v0, 0x22a00, v0
	ds_read2st64_b32 v[22:23], v0 offset1:1
	v_bitop3_b32 v0, v30, 28, 16 bitop3:0xc8
	s_ashr_i32 s41, s40, 31
	v_lshlrev_b32_e32 v0, 1, v0
	v_lshl_add_u64 v[26:27], s[40:41], 1, v[26:27]
	s_waitcnt lgkmcnt(0)
	v_add_f32_e32 v22, v22, v23
	v_fmamk_f32 v22, v22, 0x3b800000, v184
	v_mul_f32_e32 v23, 0x4b800000, v22
	v_cmp_gt_f32_e32 vcc, s90, v22
	v_lshl_add_u64 v[50:51], v[28:29], 0, v[0:1]
	s_movk_i32 s4, 0x4c
	v_cndmask_b32_e32 v22, v22, v23, vcc
	v_rsq_f32_e32 v52, v22
	v_lshl_add_u64 v[22:23], v[30:31], 1, v[26:27]
	s_add_i32 s38, s38, s96
	v_mul_f32_e32 v0, 0x45800000, v52
	v_cndmask_b32_e32 v26, v52, v0, vcc
	v_pk_mul_f32 v[42:43], v[42:43], v[26:27] op_sel_hi:[1,0]
	v_pk_mul_f32 v[44:45], v[44:45], v[26:27] op_sel_hi:[1,0]
	s_waitcnt vmcnt(0)
	v_lshlrev_b32_e32 v52, 16, v32
	v_and_b32_e32 v53, 0xffff0000, v32
	v_lshlrev_b32_e32 v32, 16, v33
	v_and_b32_e32 v33, 0xffff0000, v33
	v_max_f32_e32 v0, v52, v52
	v_max_f32_e32 v27, v53, v53
	v_max_f32_e32 v31, v32, v32
	v_max_f32_e32 v54, v33, v33
	v_max_f32_e32 v0, 0xc2a00000, v0
	v_max_f32_e32 v27, 0xc2a00000, v27
	v_max_f32_e32 v31, 0xc2a00000, v31
	v_max_f32_e32 v54, 0xc2a00000, v54
	v_mul_f32_e32 v0, 0xbfb8aa3b, v0
	v_mul_f32_e32 v27, 0xbfb8aa3b, v27
	v_mul_f32_e32 v31, 0xbfb8aa3b, v31
	v_mul_f32_e32 v54, 0xbfb8aa3b, v54
	v_exp_f32_e32 v0, v0
	v_exp_f32_e32 v27, v27
	v_exp_f32_e32 v31, v31
	v_exp_f32_e32 v54, v54
	v_add_f32_e32 v0, 1.0, v0
	v_add_f32_e32 v27, 1.0, v27
	v_add_f32_e32 v31, 1.0, v31
	v_add_f32_e32 v57, 1.0, v54
	v_rcp_f32_e32 v54, v0
	v_rcp_f32_e32 v55, v27
	v_rcp_f32_e32 v56, v31
	v_rcp_f32_e32 v57, v57
	v_pk_mul_f32 v[42:43], v[46:47], v[42:43]
	v_pk_mul_f32 v[44:45], v[48:49], v[44:45]
	v_pk_mul_f32 v[46:47], v[54:55], v[52:53]
	v_pk_mul_f32 v[32:33], v[56:57], v[32:33]
	v_pk_mul_f32 v[42:43], v[42:43], v[46:47]
	v_pk_mul_f32 v[32:33], v[44:45], v[32:33]
	v_cvt_pk_bf16_f32 v42, v42, v43
	v_cvt_pk_bf16_f32 v43, v32, v33
	flat_store_dwordx2 v[22:23], v[42:43]
	v_mov_b64_e32 v[32:33], v[90:91]
	s_nop 0
	v_mov_b64_e32 v[42:43], v[108:109]
	v_mov_b64_e32 v[44:45], v[110:111]
	v_bitop3_b32 v0, v30, 44, 32 bitop3:0xc8
	v_lshlrev_b32_e32 v0, 1, v0
	v_lshl_add_u64 v[46:47], v[28:29], 0, v[0:1]
	v_pk_mul_f32 v[38:39], v[38:39], v[26:27] op_sel_hi:[1,0]
	v_pk_mul_f32 v[40:41], v[40:41], v[26:27] op_sel_hi:[1,0]
	s_waitcnt lgkmcnt(0)
	v_lshlrev_b32_e32 v48, 16, v32
	v_and_b32_e32 v49, 0xffff0000, v32
	v_lshlrev_b32_e32 v32, 16, v33
	v_and_b32_e32 v33, 0xffff0000, v33
	v_max_f32_e32 v0, v48, v48
	v_max_f32_e32 v27, v49, v49
	v_max_f32_e32 v31, v32, v32
	v_max_f32_e32 v50, v33, v33
	v_max_f32_e32 v0, 0xc2a00000, v0
	v_max_f32_e32 v27, 0xc2a00000, v27
	v_max_f32_e32 v31, 0xc2a00000, v31
	v_max_f32_e32 v50, 0xc2a00000, v50
	v_mul_f32_e32 v0, 0xbfb8aa3b, v0
	v_mul_f32_e32 v27, 0xbfb8aa3b, v27
	v_mul_f32_e32 v31, 0xbfb8aa3b, v31
	v_mul_f32_e32 v50, 0xbfb8aa3b, v50
	v_exp_f32_e32 v0, v0
	v_exp_f32_e32 v27, v27
	v_exp_f32_e32 v31, v31
	v_exp_f32_e32 v50, v50
	v_add_f32_e32 v0, 1.0, v0
	v_add_f32_e32 v27, 1.0, v27
	v_add_f32_e32 v31, 1.0, v31
	v_add_f32_e32 v53, 1.0, v50
	v_rcp_f32_e32 v50, v0
	v_rcp_f32_e32 v51, v27
	v_rcp_f32_e32 v52, v31
	v_rcp_f32_e32 v53, v53
	v_pk_mul_f32 v[38:39], v[42:43], v[38:39]
	v_pk_mul_f32 v[40:41], v[44:45], v[40:41]
	v_pk_mul_f32 v[42:43], v[50:51], v[48:49]
	v_pk_mul_f32 v[32:33], v[52:53], v[32:33]
	v_pk_mul_f32 v[38:39], v[38:39], v[42:43]
	v_pk_mul_f32 v[32:33], v[40:41], v[32:33]
	v_cvt_pk_bf16_f32 v38, v38, v39
	v_cvt_pk_bf16_f32 v39, v32, v33
	flat_store_dwordx2 v[22:23], v[38:39] offset:32
	v_mov_b64_e32 v[32:33], v[92:93]
	s_nop 0
	v_mov_b64_e32 v[38:39], v[112:113]
	v_mov_b64_e32 v[40:41], v[114:115]
	v_bitop3_b32 v0, v30, 60, 48 bitop3:0xc8
	v_lshlrev_b32_e32 v0, 1, v0
	v_lshl_add_u64 v[42:43], v[28:29], 0, v[0:1]
	v_pk_mul_f32 v[34:35], v[34:35], v[26:27] op_sel_hi:[1,0]
	v_pk_mul_f32 v[36:37], v[36:37], v[26:27] op_sel_hi:[1,0]
	s_waitcnt lgkmcnt(0)
; __device__ __forceinline__ unsigned pk2(float lo, float hi) { const f32v2_t v = {lo, hi}; return __builtin_bit_cast(unsigned, __builtin_convertvector(v, bf16v2_t)); }
; __device__ __forceinline__ size_t pidx(int row, int col) { return (size_t)(col >> 7) * ((size_t)T * 128) + (size_t)row * 128 + (col & 127); }
; __device__ __forceinline__ float bflo(unsigned u) { return __uint_as_float(u << 16); }
; __device__ __forceinline__ float bfhi(unsigned u) { return __uint_as_float(u & 0xffff0000u); }
; __device__ __forceinline__ float siluf_(float x) { return x * __builtin_amdgcn_rcpf(1.f + __expf(-fmaxf(x, -80.f))); }
; __device__ __forceinline__ void gla3_item(const Params& p, int item, int l, unsigned char* lds) {
;     ...
;     for (int ebl = 0; ebl < 8; ++ebl) {
;         const int e = 16 * (8 * eh + ebl) + 4 * fq;
;         const u32x2 rr = *(const u32x2*)(P + pidx((int)trow, C_RG + h * 256 + e));
;         const f32x4 gn = *(const f32x4*)(ogain + e);
;         const float y0 = o[ebl][0] * rinv * gn[0] * siluf_(bflo(rr[0])), y1 = o[ebl][1] * rinv * gn[1] * siluf_(bfhi(rr[0]));
;         const float y2 = o[ebl][2] * rinv * gn[2] * siluf_(bflo(rr[1])), y3 = o[ebl][3] * rinv * gn[3] * siluf_(bfhi(rr[1]));
;         u32x2 ov = {pk2(y0, y1), pk2(y2, y3)};
;         *(u32x2*)(OG + trow * D + h * 256 + e) = ov;
;     }
	v_lshlrev_b32_e32 v44, 16, v32
	v_and_b32_e32 v45, 0xffff0000, v32
	v_lshlrev_b32_e32 v32, 16, v33
	v_and_b32_e32 v33, 0xffff0000, v33
	v_max_f32_e32 v0, v44, v44
	v_max_f32_e32 v27, v45, v45
	v_max_f32_e32 v31, v32, v32
	v_max_f32_e32 v46, v33, v33
	v_max_f32_e32 v0, 0xc2a00000, v0
	v_max_f32_e32 v27, 0xc2a00000, v27
	v_max_f32_e32 v31, 0xc2a00000, v31
	v_max_f32_e32 v46, 0xc2a00000, v46
	v_mul_f32_e32 v0, 0xbfb8aa3b, v0
	v_mul_f32_e32 v27, 0xbfb8aa3b, v27
	v_mul_f32_e32 v31, 0xbfb8aa3b, v31
	v_mul_f32_e32 v46, 0xbfb8aa3b, v46
	v_exp_f32_e32 v0, v0
	v_exp_f32_e32 v27, v27
	v_exp_f32_e32 v31, v31
	v_exp_f32_e32 v46, v46
	v_add_f32_e32 v0, 1.0, v0
	v_add_f32_e32 v27, 1.0, v27
	v_add_f32_e32 v31, 1.0, v31
	v_add_f32_e32 v49, 1.0, v46
	v_rcp_f32_e32 v46, v0
	v_rcp_f32_e32 v47, v27
	v_rcp_f32_e32 v48, v31
	v_rcp_f32_e32 v49, v49
	v_pk_mul_f32 v[34:35], v[38:39], v[34:35]
	v_pk_mul_f32 v[36:37], v[40:41], v[36:37]
	v_pk_mul_f32 v[38:39], v[46:47], v[44:45]
	v_pk_mul_f32 v[32:33], v[48:49], v[32:33]
	v_pk_mul_f32 v[34:35], v[34:35], v[38:39]
	v_pk_mul_f32 v[32:33], v[36:37], v[32:33]
	v_cvt_pk_bf16_f32 v34, v34, v35
	v_cvt_pk_bf16_f32 v35, v32, v33
	flat_store_dwordx2 v[22:23], v[34:35] offset:64
	v_mov_b64_e32 v[36:37], v[94:95]
	s_nop 0
	v_mov_b64_e32 v[32:33], v[116:117]
	v_mov_b64_e32 v[34:35], v[118:119]
	v_bitop3_b32 v0, v30, s4, 64 bitop3:0xc8
	v_lshlrev_b32_e32 v0, 1, v0
	v_lshl_add_u64 v[38:39], v[28:29], 0, v[0:1]
	v_pk_mul_f32 v[18:19], v[18:19], v[26:27] op_sel_hi:[1,0]
	v_pk_mul_f32 v[20:21], v[20:21], v[26:27] op_sel_hi:[1,0]
	s_movk_i32 s4, 0x5c
	s_waitcnt lgkmcnt(0)
	v_lshlrev_b32_e32 v40, 16, v36
	v_and_b32_e32 v41, 0xffff0000, v36
	v_lshlrev_b32_e32 v36, 16, v37
	v_and_b32_e32 v37, 0xffff0000, v37
	v_max_f32_e32 v0, v40, v40
	v_max_f32_e32 v27, v41, v41
	v_max_f32_e32 v31, v36, v36
	v_max_f32_e32 v42, v37, v37
	v_max_f32_e32 v0, 0xc2a00000, v0
	v_max_f32_e32 v27, 0xc2a00000, v27
	v_max_f32_e32 v31, 0xc2a00000, v31
	v_max_f32_e32 v42, 0xc2a00000, v42
	v_mul_f32_e32 v0, 0xbfb8aa3b, v0
	v_mul_f32_e32 v27, 0xbfb8aa3b, v27
	v_mul_f32_e32 v31, 0xbfb8aa3b, v31
	v_mul_f32_e32 v42, 0xbfb8aa3b, v42
	v_exp_f32_e32 v0, v0
	v_exp_f32_e32 v27, v27
	v_exp_f32_e32 v31, v31
	v_exp_f32_e32 v42, v42
	v_add_f32_e32 v0, 1.0, v0
	v_add_f32_e32 v27, 1.0, v27
	v_add_f32_e32 v31, 1.0, v31
	v_add_f32_e32 v45, 1.0, v42
	v_rcp_f32_e32 v42, v0
	v_rcp_f32_e32 v43, v27
	v_rcp_f32_e32 v44, v31
	v_rcp_f32_e32 v45, v45
	v_pk_mul_f32 v[18:19], v[18:19], v[32:33]
	v_pk_mul_f32 v[20:21], v[20:21], v[34:35]
	v_pk_mul_f32 v[32:33], v[42:43], v[40:41]
	v_pk_mul_f32 v[34:35], v[44:45], v[36:37]
	v_pk_mul_f32 v[18:19], v[18:19], v[32:33]
	v_pk_mul_f32 v[20:21], v[20:21], v[34:35]
	v_cvt_pk_bf16_f32 v18, v18, v19
	v_cvt_pk_bf16_f32 v19, v20, v21
	flat_store_dwordx2 v[22:23], v[18:19] offset:96
	v_mov_b64_e32 v[32:33], v[96:97]
	s_nop 0
	v_mov_b64_e32 v[18:19], v[120:121]
	v_mov_b64_e32 v[20:21], v[122:123]
	v_bitop3_b32 v0, v30, s4, v212 bitop3:0xc8
	v_lshlrev_b32_e32 v0, 1, v0
	v_lshl_add_u64 v[34:35], v[28:29], 0, v[0:1]
	v_pk_mul_f32 v[14:15], v[14:15], v[26:27] op_sel_hi:[1,0]
	v_pk_mul_f32 v[16:17], v[16:17], v[26:27] op_sel_hi:[1,0]
	s_movk_i32 s4, 0x6c
	s_waitcnt lgkmcnt(0)
	v_lshlrev_b32_e32 v36, 16, v32
	v_and_b32_e32 v37, 0xffff0000, v32
	v_lshlrev_b32_e32 v32, 16, v33
	v_and_b32_e32 v33, 0xffff0000, v33
	v_max_f32_e32 v0, v36, v36
	v_max_f32_e32 v27, v37, v37
	v_max_f32_e32 v31, v32, v32
	v_max_f32_e32 v38, v33, v33
	v_max_f32_e32 v0, 0xc2a00000, v0
	v_max_f32_e32 v27, 0xc2a00000, v27
	v_max_f32_e32 v31, 0xc2a00000, v31
	v_max_f32_e32 v38, 0xc2a00000, v38
	v_mul_f32_e32 v0, 0xbfb8aa3b, v0
	v_mul_f32_e32 v27, 0xbfb8aa3b, v27
	v_mul_f32_e32 v31, 0xbfb8aa3b, v31
	v_mul_f32_e32 v38, 0xbfb8aa3b, v38
	v_exp_f32_e32 v0, v0
	v_exp_f32_e32 v27, v27
	v_exp_f32_e32 v31, v31
	v_exp_f32_e32 v38, v38
	v_add_f32_e32 v0, 1.0, v0
	v_add_f32_e32 v27, 1.0, v27
	v_add_f32_e32 v31, 1.0, v31
	v_add_f32_e32 v41, 1.0, v38
	v_rcp_f32_e32 v38, v0
	v_rcp_f32_e32 v39, v27
	v_rcp_f32_e32 v40, v31
	v_rcp_f32_e32 v41, v41
	v_pk_mul_f32 v[14:15], v[14:15], v[18:19]
	v_pk_mul_f32 v[16:17], v[16:17], v[20:21]
	v_pk_mul_f32 v[18:19], v[38:39], v[36:37]
	v_pk_mul_f32 v[20:21], v[40:41], v[32:33]
	v_pk_mul_f32 v[14:15], v[14:15], v[18:19]
	v_pk_mul_f32 v[16:17], v[16:17], v[20:21]
	v_cvt_pk_bf16_f32 v14, v14, v15
	v_cvt_pk_bf16_f32 v15, v16, v17
	flat_store_dwordx2 v[22:23], v[14:15] offset:128
	v_mov_b64_e32 v[18:19], v[98:99]
	s_nop 0
	v_mov_b64_e32 v[14:15], v[124:125]
	v_mov_b64_e32 v[16:17], v[126:127]
	v_bitop3_b32 v0, v30, s4, v213 bitop3:0xc8
	v_lshlrev_b32_e32 v0, 1, v0
	v_lshl_add_u64 v[20:21], v[28:29], 0, v[0:1]
	v_pk_mul_f32 v[10:11], v[10:11], v[26:27] op_sel_hi:[1,0]
	v_pk_mul_f32 v[12:13], v[12:13], v[26:27] op_sel_hi:[1,0]
	s_movk_i32 s4, 0x7c
	s_waitcnt lgkmcnt(0)
; __device__ __forceinline__ unsigned pk2(float lo, float hi) { const f32v2_t v = {lo, hi}; return __builtin_bit_cast(unsigned, __builtin_convertvector(v, bf16v2_t)); }
; __device__ __forceinline__ size_t pidx(int row, int col) { return (size_t)(col >> 7) * ((size_t)T * 128) + (size_t)row * 128 + (col & 127); }
; __device__ __forceinline__ float bflo(unsigned u) { return __uint_as_float(u << 16); }
; __device__ __forceinline__ float bfhi(unsigned u) { return __uint_as_float(u & 0xffff0000u); }
; __device__ __forceinline__ float siluf_(float x) { return x * __builtin_amdgcn_rcpf(1.f + __expf(-fmaxf(x, -80.f))); }
; __device__ __forceinline__ void gla3_item(const Params& p, int item, int l, unsigned char* lds) {
;     ...
;     for (int ebl = 0; ebl < 8; ++ebl) {
;         const int e = 16 * (8 * eh + ebl) + 4 * fq;
;         const u32x2 rr = *(const u32x2*)(P + pidx((int)trow, C_RG + h * 256 + e));
;         const f32x4 gn = *(const f32x4*)(ogain + e);
;         const float y0 = o[ebl][0] * rinv * gn[0] * siluf_(bflo(rr[0])), y1 = o[ebl][1] * rinv * gn[1] * siluf_(bfhi(rr[0]));
;         const float y2 = o[ebl][2] * rinv * gn[2] * siluf_(bflo(rr[1])), y3 = o[ebl][3] * rinv * gn[3] * siluf_(bfhi(rr[1]));
;         u32x2 ov = {pk2(y0, y1), pk2(y2, y3)};
;         *(u32x2*)(OG + trow * D + h * 256 + e) = ov;
;     }
	v_lshlrev_b32_e32 v32, 16, v18
	v_and_b32_e32 v33, 0xffff0000, v18
	v_lshlrev_b32_e32 v18, 16, v19
	v_and_b32_e32 v19, 0xffff0000, v19
	v_max_f32_e32 v0, v32, v32
	v_max_f32_e32 v27, v33, v33
	v_max_f32_e32 v31, v18, v18
	v_max_f32_e32 v34, v19, v19
	v_max_f32_e32 v0, 0xc2a00000, v0
	v_max_f32_e32 v27, 0xc2a00000, v27
	v_max_f32_e32 v31, 0xc2a00000, v31
	v_max_f32_e32 v34, 0xc2a00000, v34
	v_mul_f32_e32 v0, 0xbfb8aa3b, v0
	v_mul_f32_e32 v27, 0xbfb8aa3b, v27
	v_mul_f32_e32 v31, 0xbfb8aa3b, v31
	v_mul_f32_e32 v34, 0xbfb8aa3b, v34
	v_exp_f32_e32 v0, v0
	v_exp_f32_e32 v27, v27
	v_exp_f32_e32 v31, v31
	v_exp_f32_e32 v34, v34
	v_add_f32_e32 v0, 1.0, v0
	v_add_f32_e32 v27, 1.0, v27
	v_add_f32_e32 v31, 1.0, v31
	v_add_f32_e32 v37, 1.0, v34
	v_rcp_f32_e32 v34, v0
	v_rcp_f32_e32 v35, v27
	v_rcp_f32_e32 v36, v31
	v_rcp_f32_e32 v37, v37
	v_pk_mul_f32 v[10:11], v[10:11], v[14:15]
	v_pk_mul_f32 v[12:13], v[12:13], v[16:17]
	v_pk_mul_f32 v[14:15], v[34:35], v[32:33]
	v_pk_mul_f32 v[16:17], v[36:37], v[18:19]
	v_pk_mul_f32 v[10:11], v[10:11], v[14:15]
	v_pk_mul_f32 v[12:13], v[12:13], v[16:17]
	v_cvt_pk_bf16_f32 v10, v10, v11
	v_cvt_pk_bf16_f32 v11, v12, v13
	flat_store_dwordx2 v[22:23], v[10:11] offset:160
	v_mov_b64_e32 v[14:15], v[100:101]
	s_nop 0
	v_mov_b64_e32 v[10:11], v[128:129]
	v_mov_b64_e32 v[12:13], v[130:131]
	v_bitop3_b32 v0, v30, s4, v214 bitop3:0xc8
	v_lshlrev_b32_e32 v0, 1, v0
	v_lshl_add_u64 v[16:17], v[28:29], 0, v[0:1]
	v_pk_mul_f32 v[6:7], v[6:7], v[26:27] op_sel_hi:[1,0]
	v_pk_mul_f32 v[8:9], v[8:9], v[26:27] op_sel_hi:[1,0]
	v_readlane_b32 s4, v246, 52
	s_add_i32 s12, s12, s4
	s_cmpk_gt_i32 s38, 0x1ff
	s_waitcnt lgkmcnt(0)
	v_lshlrev_b32_e32 v18, 16, v14
	v_and_b32_e32 v19, 0xffff0000, v14
	v_lshlrev_b32_e32 v14, 16, v15
	v_and_b32_e32 v15, 0xffff0000, v15
	v_max_f32_e32 v0, v18, v18
	v_max_f32_e32 v20, v19, v19
	v_max_f32_e32 v21, v14, v14
	v_max_f32_e32 v27, v15, v15
	v_max_f32_e32 v0, 0xc2a00000, v0
	v_max_f32_e32 v20, 0xc2a00000, v20
	v_max_f32_e32 v21, 0xc2a00000, v21
	v_max_f32_e32 v27, 0xc2a00000, v27
	v_mul_f32_e32 v0, 0xbfb8aa3b, v0
	v_mul_f32_e32 v20, 0xbfb8aa3b, v20
	v_mul_f32_e32 v21, 0xbfb8aa3b, v21
	v_mul_f32_e32 v27, 0xbfb8aa3b, v27
	v_exp_f32_e32 v0, v0
	v_exp_f32_e32 v20, v20
	v_exp_f32_e32 v21, v21
	v_exp_f32_e32 v27, v27
	v_add_f32_e32 v0, 1.0, v0
	v_add_f32_e32 v28, 1.0, v20
	v_add_f32_e32 v29, 1.0, v21
	v_add_f32_e32 v27, 1.0, v27
	v_rcp_f32_e32 v20, v0
	v_rcp_f32_e32 v21, v28
	v_rcp_f32_e32 v28, v29
	v_rcp_f32_e32 v29, v27
	v_pk_mul_f32 v[6:7], v[6:7], v[10:11]
	v_pk_mul_f32 v[8:9], v[8:9], v[12:13]
	v_pk_mul_f32 v[10:11], v[20:21], v[18:19]
	v_pk_mul_f32 v[12:13], v[28:29], v[14:15]
	v_pk_mul_f32 v[6:7], v[6:7], v[10:11]
	v_pk_mul_f32 v[8:9], v[8:9], v[12:13]
	v_cvt_pk_bf16_f32 v6, v6, v7
	v_cvt_pk_bf16_f32 v7, v8, v9
	flat_store_dwordx2 v[22:23], v[6:7] offset:192
	v_mov_b64_e32 v[10:11], v[102:103]
	s_nop 0
	v_mov_b64_e32 v[6:7], v[132:133]
	v_mov_b64_e32 v[8:9], v[134:135]
	v_pk_mul_f32 v[2:3], v[2:3], v[26:27] op_sel_hi:[1,0]
	v_pk_mul_f32 v[4:5], v[4:5], v[26:27] op_sel_hi:[1,0]
	s_waitcnt lgkmcnt(0)
	v_lshlrev_b32_e32 v12, 16, v10
	v_and_b32_e32 v13, 0xffff0000, v10
	v_lshlrev_b32_e32 v10, 16, v11
	v_and_b32_e32 v11, 0xffff0000, v11
	v_max_f32_e32 v0, v12, v12
	v_max_f32_e32 v14, v13, v13
	v_max_f32_e32 v15, v10, v10
	v_max_f32_e32 v16, v11, v11
	v_max_f32_e32 v0, 0xc2a00000, v0
	v_max_f32_e32 v14, 0xc2a00000, v14
	v_max_f32_e32 v15, 0xc2a00000, v15
	v_max_f32_e32 v16, 0xc2a00000, v16
	v_mul_f32_e32 v0, 0xbfb8aa3b, v0
	v_mul_f32_e32 v14, 0xbfb8aa3b, v14
	v_mul_f32_e32 v15, 0xbfb8aa3b, v15
	v_mul_f32_e32 v16, 0xbfb8aa3b, v16
	v_exp_f32_e32 v0, v0
	v_exp_f32_e32 v14, v14
	v_exp_f32_e32 v15, v15
	v_exp_f32_e32 v16, v16
	v_add_f32_e32 v0, 1.0, v0
	v_add_f32_e32 v17, 1.0, v14
	v_add_f32_e32 v18, 1.0, v15
	v_add_f32_e32 v19, 1.0, v16
	v_rcp_f32_e32 v14, v0
	v_rcp_f32_e32 v15, v17
	v_rcp_f32_e32 v16, v18
	v_rcp_f32_e32 v17, v19
	v_pk_mul_f32 v[2:3], v[2:3], v[6:7]
	v_pk_mul_f32 v[4:5], v[4:5], v[8:9]
	v_pk_mul_f32 v[6:7], v[14:15], v[12:13]
	v_pk_mul_f32 v[8:9], v[16:17], v[10:11]
	v_pk_mul_f32 v[2:3], v[2:3], v[6:7]
	v_pk_mul_f32 v[4:5], v[4:5], v[8:9]
	v_cvt_pk_bf16_f32 v2, v2, v3
	v_cvt_pk_bf16_f32 v3, v4, v5
	flat_store_dwordx2 v[22:23], v[2:3] offset:224
	s_cbranch_scc1 .LBB0_68
; __device__ __forceinline__ size_t pidx(int row, int col) { return (size_t)(col >> 7) * ((size_t)T * 128) + (size_t)row * 128 + (col & 127); }
; __device__ __forceinline__ void gla3_item(const Params& p, int item, int l, unsigned char* lds) {
;     ...
;     __syncthreads();
; #pragma unroll
;     for (int i = 0; i < 4; ++i) { const int idx = tid + 512 * i, c = idx >> 5, d4 = idx & 31; *(f32x4*)(cum + c * 128 + d4 * 4) = *(const f32x4*)(cumg + (size_t)(t0 + c) * 512 + h * 128 + d4 * 4); }
;     u32x4 rq[2], rk[2];
; #pragma unroll
;     for (int i = 0; i < 2; ++i) {
;         const int idx = tid + 512 * i, c = idx >> 4, ch = idx & 15;
;         rq[i] = *(const u32x4*)(P + pidx(t0 + c, C_QG + h * 128 + ch * 8));
;         rk[i] = *(const u32x4*)(P + pidx(t0 + c, C_KG + h * 128 + ch * 8));
;     }
.LBB0_57:
	s_lshl_b32 s4, s38, 6
	s_and_b32 s13, s4, 0x1fc0
	s_and_b32 s4, s38, 0xffffff80
	v_mov_b32_e32 v60, v185
	s_ashr_i32 s5, s4, 31
	s_lshl_b64 s[4:5], s[4:5], 2
	s_waitcnt vmcnt(0)
	v_ashrrev_i32_e32 v9, 5, v60
	s_add_u32 s4, s7, s4
	v_lshlrev_b32_e32 v0, 4, v60
	v_add_u32_e32 v2, s13, v9
	s_addc_u32 s5, s8, s5
	v_and_b32_e32 v0, 0x1f0, v0
	v_ashrrev_i32_e32 v3, 31, v2
	v_lshl_add_u64 v[6:7], s[4:5], 0, v[0:1]
	v_lshlrev_b64 v[2:3], 11, v[2:3]
	v_lshl_add_u64 v[2:3], v[6:7], 0, v[2:3]
	s_waitcnt lgkmcnt(0)
	s_barrier
	v_mov_b64_e32 v[88:89], v[2:3]
	s_mov_b64 s[4:5], 0x8000
	flat_load_dwordx4 v[2:5], v[2:3]
	v_lshl_add_u64 v[90:91], v[88:89], 0, s[4:5]
	flat_load_dwordx4 v[92:95], v[90:91]
	v_lshl_add_u64 v[90:91], v[90:91], 0, s[4:5]
	flat_load_dwordx4 v[96:99], v[90:91]
	v_lshl_add_u64 v[90:91], v[90:91], 0, s[4:5]
	flat_load_dwordx4 v[100:103], v[90:91]
	v_add_u32_e32 v10, 0x200, v60
	v_ashrrev_i32_e32 v11, 5, v10
	v_add_u32_e32 v0, 0, v0
	v_add_u32_e32 v8, s13, v11
	v_lshl_add_u32 v12, v9, 9, v0
	v_ashrrev_i32_e32 v9, 31, v8
	v_lshlrev_b64 v[8:9], 11, v[8:9]
	v_lshl_add_u64 v[8:9], v[6:7], 0, v[8:9]
	v_add_u32_e32 v63, 0x400, v60
	v_lshl_add_u32 v11, v11, 9, v0
	v_add_u32_e32 v62, 0x600, v60
	s_add_i32 s4, s38, 0x1200
	s_ashr_i32 s4, s4, 7
	s_ashr_i32 s5, s4, 31
	s_lshl_b64 s[4:5], s[4:5], 21
	s_add_u32 s4, s0, s4
	v_mov_b32_e32 v51, v1
	s_addc_u32 s5, s1, s5
	s_add_i32 s15, s38, 0x1400
	v_ashrrev_i32_e32 v59, 4, v60
	v_ashrrev_i32_e32 v64, 4, v10
	v_add_u32_e32 v10, s13, v64
	s_waitcnt vmcnt(0) lgkmcnt(0)
	ds_write_b128 v12, v[2:5]
	v_ashrrev_i32_e32 v12, 5, v63
	v_add_u32_e32 v8, s13, v12
	v_ashrrev_i32_e32 v9, 31, v8
	v_lshlrev_b64 v[8:9], 11, v[8:9]
	v_lshl_add_u64 v[8:9], v[6:7], 0, v[8:9]
	v_lshl_add_u32 v12, v12, 9, v0
	ds_write_b128 v11, v[92:95]
	v_ashrrev_i32_e32 v11, 5, v62
	v_add_u32_e32 v8, s13, v11
	v_ashrrev_i32_e32 v9, 31, v8
	v_lshlrev_b64 v[8:9], 11, v[8:9]
	v_lshl_add_u64 v[6:7], v[6:7], 0, v[8:9]
	v_add_u32_e32 v8, s13, v59
	v_ashrrev_i32_e32 v9, 31, v8
	v_lshl_add_u32 v0, v11, 9, v0
	v_lshlrev_b64 v[8:9], 8, v[8:9]
	v_ashrrev_i32_e32 v11, 31, v10
	v_lshlrev_b64 v[10:11], 8, v[10:11]
	ds_write_b128 v12, v[96:99]
	v_lshlrev_b32_e32 v2, 3, v60
	v_and_b32_e32 v52, 0x78, v2
	v_lshlrev_b32_e32 v50, 1, v52
	v_lshl_add_u64 v[12:13], s[4:5], 0, v[50:51]
	s_ashr_i32 s4, s15, 7
	s_ashr_i32 s5, s4, 31
	s_lshl_b64 s[4:5], s[4:5], 21
	s_add_u32 s4, s0, s4
	s_addc_u32 s5, s1, s5
	v_lshl_add_u64 v[14:15], v[12:13], 0, v[8:9]
	v_lshl_add_u64 v[16:17], s[4:5], 0, v[50:51]
	v_lshl_add_u64 v[12:13], v[12:13], 0, v[10:11]
	v_lshl_add_u64 v[8:9], v[16:17], 0, v[8:9]
	v_lshl_add_u64 v[10:11], v[16:17], 0, v[10:11]
	s_lshl_b32 s4, s38, 1
	v_mov_b32_e32 v3, v185
	s_and_b32 s40, s4, 0xffffff00
	ds_write_b128 v0, v[100:103]
	flat_load_dwordx4 v[46:49], v[14:15]
	flat_load_dwordx4 v[42:45], v[8:9]
	flat_load_dwordx4 v[26:29], v[12:13]
	flat_load_dwordx4 v[22:25], v[10:11]
	s_nop 0
	v_cmp_gt_i32_e32 vcc, s33, v3
	s_and_saveexec_b64 s[42:43], vcc
	s_cbranch_execz .LBB0_60
; __device__ __forceinline__ int tidx() { int t = threadIdx.x; asm volatile("" : "+v"(t)); return t; }
; __device__ __forceinline__ size_t pidx(int row, int col) { return (size_t)(col >> 7) * ((size_t)T * 128) + (size_t)row * 128 + (col & 127); }
; template <int nkeys> __device__ __forceinline__ void stage_vt(bf16_t* VT, int pitch, const bf16_t* P, int r0, int rstride, int col, int nch) {
;     const int tid = tidx();
;     for (int idx = tid; idx < nkeys * nch; idx += 512) {
;         const int key = idx % nkeys, ch = idx / nkeys;
;         const u32x4 raw = *(const u32x4*)(P + pidx(r0 + key * rstride, col + ch * 8));
;         bf16_t* d = VT + (ch * 8) * pitch + key;
;         d[0] = (bf16_t)(raw[0] & 0xffff); d[pitch] = (bf16_t)(raw[0] >> 16); d[2 * pitch] = (bf16_t)(raw[1] & 0xffff); d[3 * pitch] = (bf16_t)(raw[1] >> 16);
;         d[4 * pitch] = (bf16_t)(raw[2] & 0xffff); d[5 * pitch] = (bf16_t)(raw[2] >> 16); d[6 * pitch] = (bf16_t)(raw[3] & 0xffff); d[7 * pitch] = (bf16_t)(raw[3] >> 16);
;     }
; }
	v_readlane_b32 s15, v246, 53
	s_and_b32 s4, s12, 0x1fc0
	s_add_i32 s5, s40, 0x1600
	v_lshl_add_u32 v4, v3, 1, s15
	v_mov_b32_e32 v137, 0
	v_ashrrev_i32_e32 v136, 31, v3
	v_lshrrev_b32_e32 v136, 26, v136
	v_add_u32_e32 v136, v3, v136
	v_add_u32_e32 v138, s4, v3
	v_ashrrev_i32_e32 v144, 6, v136
	v_and_b32_e32 v136, 0xffffffc0, v136
	v_sub_u32_e32 v140, v138, v136
	v_lshl_add_u32 v136, v144, 3, s5
	v_ashrrev_i32_e32 v142, 7, v136
	v_ashrrev_i32_e32 v143, 31, v142
	v_ashrrev_i32_e32 v141, 31, v140
	v_lshlrev_b64 v[142:143], 21, v[142:143]
	v_lshlrev_b32_e32 v138, 4, v144
	v_lshlrev_b64 v[140:141], 8, v[140:141]
	v_lshl_add_u64 v[142:143], s[0:1], 0, v[142:143]
	v_and_b32_e32 v136, 0xf0, v138
	v_lshl_add_u64 v[140:141], v[142:143], 0, v[140:141]
	v_lshl_add_u64 v[140:141], v[140:141], 0, v[136:137]
	flat_load_dwordx4 v[120:123], v[140:141]
	v_lshl_add_u32 v145, v144, 10, v4
	v_add_u32_e32 v158, 0x200, v3
	v_mov_b32_e32 v149, 0
	v_ashrrev_i32_e32 v148, 31, v158
	v_lshrrev_b32_e32 v148, 26, v148
	v_add_u32_e32 v148, v158, v148
	v_add_u32_e32 v150, s4, v158
	v_ashrrev_i32_e32 v156, 6, v148
	v_and_b32_e32 v148, 0xffffffc0, v148
	v_sub_u32_e32 v152, v150, v148
	v_lshl_add_u32 v148, v156, 3, s5
	v_ashrrev_i32_e32 v154, 7, v148
	v_ashrrev_i32_e32 v155, 31, v154
	v_ashrrev_i32_e32 v153, 31, v152
	v_lshlrev_b64 v[154:155], 21, v[154:155]
	v_lshlrev_b32_e32 v150, 4, v156
	v_lshlrev_b64 v[152:153], 8, v[152:153]
	v_lshl_add_u64 v[154:155], s[0:1], 0, v[154:155]
	v_and_b32_e32 v148, 0xf0, v150
	v_lshl_add_u64 v[152:153], v[154:155], 0, v[152:153]
	v_lshl_add_u64 v[152:153], v[152:153], 0, v[148:149]
	flat_load_dwordx4 v[124:127], v[152:153]
	v_add_u32_e32 v157, 0x400, v4
	v_lshl_add_u32 v157, v156, 10, v157
	v_add_u32_e32 v170, 0x400, v3
	v_mov_b32_e32 v161, 0
	v_ashrrev_i32_e32 v160, 31, v170
	v_lshrrev_b32_e32 v160, 26, v160
	v_add_u32_e32 v160, v170, v160
	v_add_u32_e32 v162, s4, v170
	v_ashrrev_i32_e32 v168, 6, v160
	v_and_b32_e32 v160, 0xffffffc0, v160
	v_sub_u32_e32 v164, v162, v160
	v_lshl_add_u32 v160, v168, 3, s5
	v_ashrrev_i32_e32 v166, 7, v160
	v_ashrrev_i32_e32 v167, 31, v166
	v_ashrrev_i32_e32 v165, 31, v164
	v_lshlrev_b64 v[166:167], 21, v[166:167]
	v_lshlrev_b32_e32 v162, 4, v168
	v_lshlrev_b64 v[164:165], 8, v[164:165]
	v_lshl_add_u64 v[166:167], s[0:1], 0, v[166:167]
	v_and_b32_e32 v160, 0xf0, v162
	v_lshl_add_u64 v[164:165], v[166:167], 0, v[164:165]
	v_lshl_add_u64 v[164:165], v[164:165], 0, v[160:161]
	flat_load_dwordx4 v[128:131], v[164:165]
	v_add_u32_e32 v169, 0x800, v4
	v_lshl_add_u32 v169, v168, 10, v169
	v_add_u32_e32 v182, 0x600, v3
	v_mov_b32_e32 v173, 0
	v_ashrrev_i32_e32 v172, 31, v182
	v_lshrrev_b32_e32 v172, 26, v172
	v_add_u32_e32 v172, v182, v172
	v_add_u32_e32 v174, s4, v182
	v_ashrrev_i32_e32 v180, 6, v172
	v_and_b32_e32 v172, 0xffffffc0, v172
	v_sub_u32_e32 v176, v174, v172
	v_lshl_add_u32 v172, v180, 3, s5
	v_ashrrev_i32_e32 v178, 7, v172
	v_ashrrev_i32_e32 v179, 31, v178
	v_ashrrev_i32_e32 v177, 31, v176
	v_lshlrev_b64 v[178:179], 21, v[178:179]
	v_lshlrev_b32_e32 v174, 4, v180
	v_lshlrev_b64 v[176:177], 8, v[176:177]
	v_lshl_add_u64 v[178:179], s[0:1], 0, v[178:179]
	v_and_b32_e32 v172, 0xf0, v174
	v_lshl_add_u64 v[176:177], v[178:179], 0, v[176:177]
	v_lshl_add_u64 v[176:177], v[176:177], 0, v[172:173]
	flat_load_dwordx4 v[132:135], v[176:177]
	v_add_u32_e32 v181, 0xc00, v4
	v_lshl_add_u32 v181, v180, 10, v181
	s_waitcnt vmcnt(0) lgkmcnt(0)
	ds_write_b16 v145, v120
	ds_write_b16_d16_hi v145, v120 offset:144
	ds_write_b16 v145, v121 offset:288
	ds_write_b16_d16_hi v145, v121 offset:432
	ds_write_b16 v145, v122 offset:576
	ds_write_b16_d16_hi v145, v122 offset:720
	ds_write_b16 v145, v123 offset:864
	ds_write_b16_d16_hi v145, v123 offset:1008
	ds_write_b16 v157, v124
	ds_write_b16_d16_hi v157, v124 offset:144
	ds_write_b16 v157, v125 offset:288
	ds_write_b16_d16_hi v157, v125 offset:432
	ds_write_b16 v157, v126 offset:576
	ds_write_b16_d16_hi v157, v126 offset:720
	ds_write_b16 v157, v127 offset:864
	ds_write_b16_d16_hi v157, v127 offset:1008
	ds_write_b16 v169, v128
	ds_write_b16_d16_hi v169, v128 offset:144
	ds_write_b16 v169, v129 offset:288
	ds_write_b16_d16_hi v169, v129 offset:432
	ds_write_b16 v169, v130 offset:576
	ds_write_b16_d16_hi v169, v130 offset:720
	ds_write_b16 v169, v131 offset:864
	ds_write_b16_d16_hi v169, v131 offset:1008
	ds_write_b16 v181, v132
	ds_write_b16_d16_hi v181, v132 offset:144
	ds_write_b16 v181, v133 offset:288
	ds_write_b16_d16_hi v181, v133 offset:432
	ds_write_b16 v181, v134 offset:576
	ds_write_b16_d16_hi v181, v134 offset:720
	ds_write_b16 v181, v135 offset:864
	ds_write_b16_d16_hi v181, v135 offset:1008

; __device__ __forceinline__ void gla1_item(const Params& p, int item, int l, unsigned char* lds) {
;     ...
;     {
;         const int d = tid & 127, c0 = tid >> 7;
;         float wv[16];
; #pragma unroll
;         for (int q = 0; q < 16; ++q) wv[q] = wa[q * 512 + h * 128 + d];
;         const float bias = ba[h * 128 + d];
; #pragma unroll 4
;         for (int i = 0; i < 16; ++i) {
;             const int c = c0 + 4 * i;
;             const float* ar = agla + (size_t)(t0 + c) * 16;
;             float a = bias;
; #pragma unroll
;             for (int q4 = 0; q4 < 4; ++q4) { const f32x4 t4 = *(const f32x4*)(ar + q4 * 4); a += t4[0] * wv[q4 * 4] + t4[1] * wv[q4 * 4 + 1] + t4[2] * wv[q4 * 4 + 2] + t4[3] * wv[q4 * 4 + 3]; }
;             const float ls = fminf(a, 0.f) - __logf(1.f + __expf(-fabsf(a)));
;             cum[c * 128 + d] = ls * (1.f / 16.f);
;         }
.LBB0_88:
	v_lshl_add_u64 v[228:229], v[28:29], 0, s[0:1]
	v_add_co_u32_e32 v228, vcc, 0x24e18000, v228
	s_nop 1
	v_addc_co_u32_e32 v229, vcc, 0, v229, vcc
	s_nop 0
	global_load_dwordx4 v[152:155], v[228:229], off
	global_load_dwordx4 v[156:159], v[228:229], off offset:16
	global_load_dwordx4 v[160:163], v[228:229], off offset:32
	global_load_dwordx4 v[164:167], v[228:229], off offset:48
	v_lshl_add_u64 v[228:229], v[26:27], 0, s[0:1]
	v_add_co_u32_e32 v228, vcc, 0x24e18000, v228
	s_nop 1
	v_addc_co_u32_e32 v229, vcc, 0, v229, vcc
	s_nop 0
	global_load_dwordx4 v[168:171], v[228:229], off
	global_load_dwordx4 v[172:175], v[228:229], off offset:16
	global_load_dwordx4 v[176:179], v[228:229], off offset:32
	global_load_dwordx4 v[180:183], v[228:229], off offset:48
	v_lshl_add_u64 v[228:229], v[24:25], 0, s[0:1]
	v_add_co_u32_e32 v228, vcc, 0x24e18000, v228
	s_nop 1
	v_addc_co_u32_e32 v229, vcc, 0, v229, vcc
	s_nop 0
	global_load_dwordx4 v[186:189], v[228:229], off
	global_load_dwordx4 v[190:193], v[228:229], off offset:16
	global_load_dwordx4 v[194:197], v[228:229], off offset:32
	global_load_dwordx4 v[198:201], v[228:229], off offset:48
	v_lshl_add_u64 v[228:229], v[22:23], 0, s[0:1]
	v_add_co_u32_e32 v228, vcc, 0x24e18000, v228
	s_nop 1
	v_addc_co_u32_e32 v229, vcc, 0, v229, vcc
	s_nop 0
	global_load_dwordx4 v[202:205], v[228:229], off
	global_load_dwordx4 v[206:209], v[228:229], off offset:16
	global_load_dwordx4 v[220:223], v[228:229], off offset:32
	global_load_dwordx4 v[224:227], v[228:229], off offset:48
	v_lshl_add_u64 v[32:33], v[28:29], 0, s[0:1]
	v_add_co_u32_e32 v44, vcc, 0x24e18000, v32
	v_lshl_add_u64 v[48:49], v[26:27], 0, s[0:1]
	s_nop 0
	v_addc_co_u32_e32 v45, vcc, 0, v33, vcc
	s_nop 0
	v_add_co_u32_e32 v48, vcc, s17, v48
	s_waitcnt vmcnt(0) lgkmcnt(0)
	v_mov_b64_e32 v[32:33], v[152:153]
	v_mov_b64_e32 v[34:35], v[154:155]
	v_mov_b64_e32 v[36:37], v[156:157]
	v_mov_b64_e32 v[38:39], v[158:159]
	v_mov_b64_e32 v[40:41], v[160:161]
	v_mov_b64_e32 v[42:43], v[162:163]
	v_mov_b64_e32 v[44:45], v[164:165]
	v_mov_b64_e32 v[46:47], v[166:167]
	v_mov_b32_e32 v50, v32
	v_mov_b32_e32 v51, v36
	v_mov_b32_e32 v36, v33
	v_pk_mul_f32 v[36:37], v[10:11], v[36:37]
	v_mov_b32_e32 v32, v34
	v_mov_b32_e32 v33, v38
	v_mov_b32_e32 v38, v35
	v_mov_b32_e32 v35, v44
	v_mov_b32_e32 v44, v41
	v_pk_fma_f32 v[36:37], v[8:9], v[50:51], v[36:37]
	v_mov_b32_e32 v34, v40
	v_mov_b32_e32 v40, v42
	v_mov_b32_e32 v41, v46
	v_mov_b32_e32 v46, v43
	v_pk_mul_f32 v[42:43], v[14:15], v[44:45]
	v_pk_fma_f32 v[32:33], v[6:7], v[32:33], v[36:37]
	v_pk_fma_f32 v[34:35], v[12:13], v[34:35], v[42:43]
	v_pk_fma_f32 v[32:33], v[18:19], v[38:39], v[32:33]
	v_pk_fma_f32 v[34:35], v[16:17], v[40:41], v[34:35]
	v_add_f32_e32 v3, v0, v32
	v_pk_fma_f32 v[34:35], v[20:21], v[46:47], v[34:35]
	v_add_f32_e32 v3, v3, v33
	v_add_f32_e32 v3, v3, v34
	v_add_f32_e32 v3, v3, v35
	v_min_f32_e32 v32, 0, v3
	v_mul_f32_e64 v3, |v3|, s28
	v_exp_f32_e32 v3, v3
	v_addc_co_u32_e32 v49, vcc, 0, v49, vcc
	v_add_f32_e32 v3, 1.0, v3
	v_cmp_gt_f32_e32 vcc, s90, v3
	s_nop 1
	v_cndmask_b32_e64 v33, 0, 32, vcc
	v_ldexp_f32 v3, v3, v33
	v_log_f32_e32 v3, v3
	v_cndmask_b32_e32 v34, 0, v215, vcc
	v_mul_f32_e32 v33, 0x3f317217, v3
	v_fma_f32 v33, v3, s93, -v33
	v_fmac_f32_e32 v33, 0x3377d1cf, v3
	v_cmp_lt_f32_e64 vcc, |v3|, s18
	v_fmac_f32_e32 v33, 0x3f317217, v3
	s_nop 0
	v_cndmask_b32_e32 v3, v3, v33, vcc
	v_sub_f32_e32 v3, v3, v34
	v_sub_f32_e32 v3, v32, v3
	v_mul_f32_e32 v3, 0x3d800000, v3
	ds_write_b32 v5, v3
	v_mov_b64_e32 v[32:33], v[168:169]
	v_mov_b64_e32 v[34:35], v[170:171]
	v_mov_b64_e32 v[36:37], v[172:173]
	v_mov_b64_e32 v[38:39], v[174:175]
	v_mov_b64_e32 v[40:41], v[176:177]
	v_mov_b64_e32 v[42:43], v[178:179]
	v_mov_b64_e32 v[44:45], v[180:181]
	v_mov_b64_e32 v[46:47], v[182:183]
	v_lshl_add_u64 v[48:49], v[24:25], 0, s[0:1]
	v_add_co_u32_e32 v48, vcc, s17, v48
	s_waitcnt lgkmcnt(0)
	v_mov_b32_e32 v50, v32
	v_mov_b32_e32 v51, v36
	v_mov_b32_e32 v36, v33
	v_pk_mul_f32 v[36:37], v[10:11], v[36:37]
	v_mov_b32_e32 v32, v34
	v_mov_b32_e32 v33, v38
	v_mov_b32_e32 v38, v35
	v_mov_b32_e32 v35, v44
	v_mov_b32_e32 v44, v41
	v_pk_fma_f32 v[36:37], v[8:9], v[50:51], v[36:37]
	v_mov_b32_e32 v34, v40
	v_mov_b32_e32 v40, v42
	v_mov_b32_e32 v41, v46
	v_mov_b32_e32 v46, v43
	v_pk_mul_f32 v[42:43], v[14:15], v[44:45]
	v_pk_fma_f32 v[32:33], v[6:7], v[32:33], v[36:37]
	v_pk_fma_f32 v[34:35], v[12:13], v[34:35], v[42:43]
	v_pk_fma_f32 v[32:33], v[18:19], v[38:39], v[32:33]
	v_pk_fma_f32 v[34:35], v[16:17], v[40:41], v[34:35]
	v_add_f32_e32 v3, v0, v32
	v_pk_fma_f32 v[34:35], v[20:21], v[46:47], v[34:35]
	v_add_f32_e32 v3, v3, v33
	v_add_f32_e32 v3, v3, v34
	v_add_f32_e32 v3, v3, v35
	v_min_f32_e32 v32, 0, v3
	v_mul_f32_e64 v3, |v3|, s28
	v_exp_f32_e32 v3, v3
	v_addc_co_u32_e32 v49, vcc, 0, v49, vcc
	v_add_f32_e32 v3, 1.0, v3
	v_cmp_gt_f32_e32 vcc, s90, v3
	s_nop 1
	v_cndmask_b32_e64 v33, 0, 32, vcc
	v_ldexp_f32 v3, v3, v33
	v_log_f32_e32 v3, v3
	v_cndmask_b32_e32 v34, 0, v215, vcc
	v_mul_f32_e32 v33, 0x3f317217, v3
	v_fma_f32 v33, v3, s93, -v33
	v_fmac_f32_e32 v33, 0x3377d1cf, v3
	v_cmp_lt_f32_e64 vcc, |v3|, s18
	v_fmac_f32_e32 v33, 0x3f317217, v3
	s_nop 0
	v_cndmask_b32_e32 v3, v3, v33, vcc
	v_sub_f32_e32 v3, v3, v34
	v_sub_f32_e32 v3, v32, v3
	v_mul_f32_e32 v3, 0x3d800000, v3
	ds_write_b32 v5, v3 offset:2048
	v_mov_b64_e32 v[32:33], v[186:187]
	v_mov_b64_e32 v[34:35], v[188:189]
	v_mov_b64_e32 v[36:37], v[190:191]
	v_mov_b64_e32 v[38:39], v[192:193]
	v_mov_b64_e32 v[40:41], v[194:195]
	v_mov_b64_e32 v[42:43], v[196:197]
	v_mov_b64_e32 v[44:45], v[198:199]
	v_mov_b64_e32 v[46:47], v[200:201]
	v_lshl_add_u64 v[48:49], v[22:23], 0, s[0:1]
	v_add_co_u32_e32 v48, vcc, s17, v48
	s_add_u32 s0, s0, 0x400
	s_nop 0
	v_addc_co_u32_e32 v49, vcc, 0, v49, vcc
	s_addc_u32 s1, s1, 0
	s_cmpk_eq_i32 s0, 0x1000
	s_waitcnt lgkmcnt(0)
; __device__ __forceinline__ size_t pidx(int row, int col) { return (size_t)(col >> 7) * ((size_t)T * 128) + (size_t)row * 128 + (col & 127); }
; __device__ __forceinline__ void gla1_item(const Params& p, int item, int l, unsigned char* lds) {
;     ...
; #pragma unroll 4
;         for (int i = 0; i < 16; ++i) {
;             const int c = c0 + 4 * i;
;             const float* ar = agla + (size_t)(t0 + c) * 16;
;             float a = bias;
; #pragma unroll
;             for (int q4 = 0; q4 < 4; ++q4) { const f32x4 t4 = *(const f32x4*)(ar + q4 * 4); a += t4[0] * wv[q4 * 4] + t4[1] * wv[q4 * 4 + 1] + t4[2] * wv[q4 * 4 + 2] + t4[3] * wv[q4 * 4 + 3]; }
;             const float ls = fminf(a, 0.f) - __logf(1.f + __expf(-fabsf(a)));
;             cum[c * 128 + d] = ls * (1.f / 16.f);
;         }
;     }
;     for (int idx = tid; idx < 1024; idx += 512) {
;         const int r = idx >> 4, ch = idx & 15;
;         *(u32x4*)(Kr + r * 136 + ch * 8) = *(const u32x4*)(P + pidx(t0 + r, C_KG + h * 128 + ch * 8));
;     }
	v_mov_b32_e32 v50, v32
	v_mov_b32_e32 v51, v36
	v_mov_b32_e32 v36, v33
	v_pk_mul_f32 v[36:37], v[10:11], v[36:37]
	v_mov_b32_e32 v32, v34
	v_mov_b32_e32 v33, v38
	v_mov_b32_e32 v38, v35
	v_mov_b32_e32 v35, v44
	v_mov_b32_e32 v44, v41
	v_pk_fma_f32 v[36:37], v[8:9], v[50:51], v[36:37]
	v_mov_b32_e32 v34, v40
	v_mov_b32_e32 v40, v42
	v_mov_b32_e32 v41, v46
	v_mov_b32_e32 v46, v43
	v_pk_mul_f32 v[42:43], v[14:15], v[44:45]
	v_pk_fma_f32 v[32:33], v[6:7], v[32:33], v[36:37]
	v_pk_fma_f32 v[34:35], v[12:13], v[34:35], v[42:43]
	v_pk_fma_f32 v[32:33], v[18:19], v[38:39], v[32:33]
	v_pk_fma_f32 v[34:35], v[16:17], v[40:41], v[34:35]
	v_add_f32_e32 v3, v0, v32
	v_pk_fma_f32 v[34:35], v[20:21], v[46:47], v[34:35]
	v_add_f32_e32 v3, v3, v33
	v_add_f32_e32 v3, v3, v34
	v_add_f32_e32 v3, v3, v35
	v_min_f32_e32 v32, 0, v3
	v_mul_f32_e64 v3, |v3|, s28
	v_exp_f32_e32 v3, v3
	s_nop 0
	v_add_f32_e32 v3, 1.0, v3
	v_cmp_gt_f32_e32 vcc, s90, v3
	s_nop 1
	v_cndmask_b32_e64 v33, 0, 32, vcc
	v_ldexp_f32 v3, v3, v33
	v_log_f32_e32 v3, v3
	v_cndmask_b32_e32 v34, 0, v215, vcc
	v_mul_f32_e32 v33, 0x3f317217, v3
	v_fma_f32 v33, v3, s93, -v33
	v_fmac_f32_e32 v33, 0x3377d1cf, v3
	v_cmp_lt_f32_e64 vcc, |v3|, s18
	v_fmac_f32_e32 v33, 0x3f317217, v3
	s_nop 0
	v_cndmask_b32_e32 v3, v3, v33, vcc
	v_sub_f32_e32 v3, v3, v34
	v_sub_f32_e32 v3, v32, v3
	v_mul_f32_e32 v3, 0x3d800000, v3
	ds_write_b32 v5, v3 offset:4096
	v_mov_b64_e32 v[32:33], v[202:203]
	v_mov_b64_e32 v[34:35], v[204:205]
	v_mov_b64_e32 v[36:37], v[206:207]
	v_mov_b64_e32 v[38:39], v[208:209]
	v_mov_b64_e32 v[40:41], v[220:221]
	v_mov_b64_e32 v[42:43], v[222:223]
	v_mov_b64_e32 v[44:45], v[224:225]
	v_mov_b64_e32 v[46:47], v[226:227]
	s_waitcnt lgkmcnt(0)
	v_mov_b32_e32 v48, v32
	v_mov_b32_e32 v49, v36
	v_mov_b32_e32 v36, v33
	v_pk_mul_f32 v[36:37], v[10:11], v[36:37]
	v_mov_b32_e32 v32, v34
	v_mov_b32_e32 v33, v38
	v_mov_b32_e32 v38, v35
	v_mov_b32_e32 v35, v44
	v_mov_b32_e32 v44, v41
	v_pk_fma_f32 v[36:37], v[8:9], v[48:49], v[36:37]
	v_mov_b32_e32 v34, v40
	v_mov_b32_e32 v40, v42
	v_mov_b32_e32 v41, v46
	v_mov_b32_e32 v46, v43
	v_pk_mul_f32 v[42:43], v[14:15], v[44:45]
	v_pk_fma_f32 v[32:33], v[6:7], v[32:33], v[36:37]
	v_pk_fma_f32 v[34:35], v[12:13], v[34:35], v[42:43]
	v_pk_fma_f32 v[32:33], v[18:19], v[38:39], v[32:33]
	v_pk_fma_f32 v[34:35], v[16:17], v[40:41], v[34:35]
	v_add_f32_e32 v3, v0, v32
	v_pk_fma_f32 v[34:35], v[20:21], v[46:47], v[34:35]
	v_add_f32_e32 v3, v3, v33
	v_add_f32_e32 v3, v3, v34
	v_add_f32_e32 v3, v3, v35
	v_mul_f32_e64 v32, |v3|, s28
	v_exp_f32_e32 v32, v32
	v_min_f32_e32 v3, 0, v3
	v_add_f32_e32 v32, 1.0, v32
	v_cmp_gt_f32_e32 vcc, s90, v32
	s_nop 1
	v_cndmask_b32_e64 v33, 0, 32, vcc
	v_ldexp_f32 v32, v32, v33
	v_log_f32_e32 v32, v32
	v_cndmask_b32_e32 v33, 0, v215, vcc
	v_mul_f32_e32 v34, 0x3f317217, v32
	v_fma_f32 v34, v32, s93, -v34
	v_fmac_f32_e32 v34, 0x3377d1cf, v32
	v_cmp_lt_f32_e64 vcc, |v32|, s18
	v_fmac_f32_e32 v34, 0x3f317217, v32
	s_nop 0
	v_cndmask_b32_e32 v32, v32, v34, vcc
	v_sub_f32_e32 v32, v32, v33
	v_sub_f32_e32 v3, v3, v32
	v_mul_f32_e32 v3, 0x3d800000, v3
	ds_write_b32 v5, v3 offset:6144
	v_add_u32_e32 v5, 0x2000, v5
	s_cbranch_scc0 .LBB0_88
	s_lshl_b32 s0, s4, 6
	s_and_b32 s17, s0, 0x1fc0
	s_movk_i32 s0, 0x400
	v_cmp_gt_i32_e64 s[36:37], s0, v30
	s_and_saveexec_b64 s[0:1], s[36:37]
	s_movk_i32 s25, 0x110
	s_cbranch_execz .LBB0_92
	s_lshl_b32 s18, s4, 14
	s_and_b32 s18, s18, 0x600000
	s_add_u32 s38, s2, s18
	s_addc_u32 s39, s3, 0
	v_lshlrev_b32_e32 v3, 3, v30
	v_mov_b32_e32 v177, 0
	v_lshlrev_b32_e32 v176, 1, v3
	v_ashrrev_i32_e32 v186, 4, v30
	v_add_u32_e32 v178, s17, v186
	v_ashrrev_i32_e32 v179, 31, v178
	v_lshlrev_b64 v[178:179], 8, v[178:179]
	v_and_b32_e32 v176, 0xf0, v176
	v_lshl_add_u64 v[178:179], s[38:39], 0, v[178:179]
	v_lshl_add_u64 v[178:179], v[178:179], 0, v[176:177]
	v_add_co_u32_e32 v178, vcc, 0x5000000, v178
	s_nop 1
	v_addc_co_u32_e32 v179, vcc, 0, v179, vcc
	s_nop 0
	flat_load_dwordx4 v[152:155], v[178:179]
	v_mul_lo_u32 v186, v186, s25
	v_add3_u32 v187, 0, v186, v176
	v_add_u32_e32 v188, 0x200, v30
	v_add_u32_e32 v189, 0x1000, v3
	v_mov_b32_e32 v181, 0
	v_lshlrev_b32_e32 v180, 1, v189
	v_ashrrev_i32_e32 v188, 4, v188
	v_add_u32_e32 v182, s17, v188
	v_ashrrev_i32_e32 v183, 31, v182
	v_lshlrev_b64 v[182:183], 8, v[182:183]
	v_and_b32_e32 v180, 0xf0, v180
	v_lshl_add_u64 v[182:183], s[38:39], 0, v[182:183]
	v_lshl_add_u64 v[182:183], v[182:183], 0, v[180:181]
	v_add_co_u32_e32 v182, vcc, 0x5000000, v182
	s_nop 1
	v_addc_co_u32_e32 v183, vcc, 0, v183, vcc
	s_nop 0
	flat_load_dwordx4 v[156:159], v[182:183]
	v_mul_lo_u32 v188, v188, s25
	v_add3_u32 v189, 0, v188, v180
; __device__ __forceinline__ int tidx() { int t = threadIdx.x; asm volatile("" : "+v"(t)); return t; }
; __device__ __forceinline__ size_t pidx(int row, int col) { return (size_t)(col >> 7) * ((size_t)T * 128) + (size_t)row * 128 + (col & 127); }
; template <int nkeys> __device__ __forceinline__ void stage_vt(bf16_t* VT, int pitch, const bf16_t* P, int r0, int rstride, int col, int nch) {
;     const int tid = tidx();
;     for (int idx = tid; idx < nkeys * nch; idx += 512) {
;         const int key = idx % nkeys, ch = idx / nkeys;
;         const u32x4 raw = *(const u32x4*)(P + pidx(r0 + key * rstride, col + ch * 8));
;         bf16_t* d = VT + (ch * 8) * pitch + key;
;         d[0] = (bf16_t)(raw[0] & 0xffff); d[pitch] = (bf16_t)(raw[0] >> 16); d[2 * pitch] = (bf16_t)(raw[1] & 0xffff); d[3 * pitch] = (bf16_t)(raw[1] >> 16);
;         d[4 * pitch] = (bf16_t)(raw[2] & 0xffff); d[5 * pitch] = (bf16_t)(raw[2] >> 16); d[6 * pitch] = (bf16_t)(raw[3] & 0xffff); d[7 * pitch] = (bf16_t)(raw[3] >> 16);
;     }
; }
; __device__ __forceinline__ void gla1_item(const Params& p, int item, int l, unsigned char* lds) {
;     ...
;     for (int idx = tid; idx < 1024; idx += 512) {
;         const int r = idx >> 4, ch = idx & 15;
;         *(u32x4*)(Kr + r * 136 + ch * 8) = *(const u32x4*)(P + pidx(t0 + r, C_KG + h * 128 + ch * 8));
;     }
;     stage_vt<64>(VT, 72, P, t0, 1, C_VG + h * 256, 32);
.LBB0_92:
	s_movk_i32 s25, 0x110
	s_or_b64 exec, exec, s[0:1]
	v_mov_b32_e32 v3, v185
	s_nop 0
	v_cmp_gt_i32_e32 vcc, s33, v3
	s_and_saveexec_b64 s[0:1], vcc
	s_cbranch_execz .LBB0_95
	s_lshl_b32 s18, s4, 1
	s_and_b32 s18, s18, 0x300
	v_readlane_b32 s19, v246, 57
	s_addk_i32 s18, 0x1600
	v_lshl_add_u32 v5, v3, 1, s19
	v_mov_b32_e32 v191, 0
	v_ashrrev_i32_e32 v190, 31, v3
	v_lshrrev_b32_e32 v190, 26, v190
	v_add_u32_e32 v190, v3, v190
	v_add_u32_e32 v192, s16, v3
	v_ashrrev_i32_e32 v196, 6, v190
	v_and_b32_e32 v190, 0xffffffc0, v190
	v_sub_u32_e32 v192, v192, v190
	v_lshl_add_u32 v190, v196, 3, s18
	v_lshlrev_b32_e32 v199, 4, v196
	v_ashrrev_i32_e32 v194, 7, v190
	v_and_b32_e32 v190, 0xf0, v199
	v_ashrrev_i32_e32 v195, 31, v194
	v_ashrrev_i32_e32 v193, 31, v192
	v_lshlrev_b64 v[194:195], 21, v[194:195]
	v_lshlrev_b64 v[192:193], 8, v[192:193]
	v_lshl_add_u64 v[194:195], s[2:3], 0, v[194:195]
	v_lshl_add_u64 v[192:193], v[194:195], 0, v[192:193]
	v_lshl_add_u64 v[192:193], v[192:193], 0, v[190:191]
	flat_load_dwordx4 v[160:163], v[192:193]
	v_lshl_add_u32 v197, v196, 10, v5
	v_add_u32_e32 v208, 0x200, v3
	v_mov_b32_e32 v201, 0
	v_ashrrev_i32_e32 v200, 31, v208
	v_lshrrev_b32_e32 v200, 26, v200
	v_add_u32_e32 v200, v208, v200
	v_add_u32_e32 v202, s16, v208
	v_ashrrev_i32_e32 v206, 6, v200
	v_and_b32_e32 v200, 0xffffffc0, v200
	v_sub_u32_e32 v202, v202, v200
	v_lshl_add_u32 v200, v206, 3, s18
	v_lshlrev_b32_e32 v209, 4, v206
	v_ashrrev_i32_e32 v204, 7, v200
	v_and_b32_e32 v200, 0xf0, v209
	v_ashrrev_i32_e32 v205, 31, v204
	v_ashrrev_i32_e32 v203, 31, v202
	v_lshlrev_b64 v[204:205], 21, v[204:205]
	v_lshlrev_b64 v[202:203], 8, v[202:203]
	v_lshl_add_u64 v[204:205], s[2:3], 0, v[204:205]
	v_lshl_add_u64 v[202:203], v[204:205], 0, v[202:203]
	v_lshl_add_u64 v[202:203], v[202:203], 0, v[200:201]
	flat_load_dwordx4 v[164:167], v[202:203]
	v_add_u32_e32 v207, 0x400, v5
	v_lshl_add_u32 v207, v206, 10, v207
	v_add_u32_e32 v228, 0x400, v3
	v_mov_b32_e32 v221, 0
	v_ashrrev_i32_e32 v220, 31, v228
	v_lshrrev_b32_e32 v220, 26, v220
	v_add_u32_e32 v220, v228, v220
	v_add_u32_e32 v222, s16, v228
	v_ashrrev_i32_e32 v226, 6, v220
	v_and_b32_e32 v220, 0xffffffc0, v220
	v_sub_u32_e32 v222, v222, v220
	v_lshl_add_u32 v220, v226, 3, s18
	v_lshlrev_b32_e32 v229, 4, v226
	v_ashrrev_i32_e32 v224, 7, v220
	v_and_b32_e32 v220, 0xf0, v229
	v_ashrrev_i32_e32 v225, 31, v224
	v_ashrrev_i32_e32 v223, 31, v222
	v_lshlrev_b64 v[224:225], 21, v[224:225]
	v_lshlrev_b64 v[222:223], 8, v[222:223]
	v_lshl_add_u64 v[224:225], s[2:3], 0, v[224:225]
	v_lshl_add_u64 v[222:223], v[224:225], 0, v[222:223]
	v_lshl_add_u64 v[222:223], v[222:223], 0, v[220:221]
	flat_load_dwordx4 v[168:171], v[222:223]
	v_add_u32_e32 v227, 0x800, v5
	v_lshl_add_u32 v227, v226, 10, v227
	v_add_u32_e32 v238, 0x600, v3
	v_mov_b32_e32 v231, 0
	v_ashrrev_i32_e32 v230, 31, v238
	v_lshrrev_b32_e32 v230, 26, v230
	v_add_u32_e32 v230, v238, v230
	v_add_u32_e32 v232, s16, v238
	v_ashrrev_i32_e32 v236, 6, v230
	v_and_b32_e32 v230, 0xffffffc0, v230
	v_sub_u32_e32 v232, v232, v230
	v_lshl_add_u32 v230, v236, 3, s18
	v_lshlrev_b32_e32 v239, 4, v236
	v_ashrrev_i32_e32 v234, 7, v230
	v_and_b32_e32 v230, 0xf0, v239
	v_ashrrev_i32_e32 v235, 31, v234
	v_ashrrev_i32_e32 v233, 31, v232
	v_lshlrev_b64 v[234:235], 21, v[234:235]
	v_lshlrev_b64 v[232:233], 8, v[232:233]
	v_lshl_add_u64 v[234:235], s[2:3], 0, v[234:235]
	v_lshl_add_u64 v[232:233], v[234:235], 0, v[232:233]
	v_lshl_add_u64 v[232:233], v[232:233], 0, v[230:231]
	flat_load_dwordx4 v[172:175], v[232:233]
	v_add_u32_e32 v237, 0xc00, v5
	v_lshl_add_u32 v237, v236, 10, v237
	s_waitcnt vmcnt(0) lgkmcnt(0)
	ds_write_b128 v187, v[152:155] offset:32768
	ds_write_b128 v189, v[156:159] offset:32768
	ds_write_b16 v197, v160
	ds_write_b16_d16_hi v197, v160 offset:144
	ds_write_b16 v197, v161 offset:288
	ds_write_b16_d16_hi v197, v161 offset:432
	ds_write_b16 v197, v162 offset:576
	ds_write_b16_d16_hi v197, v162 offset:720
	ds_write_b16 v197, v163 offset:864
	ds_write_b16_d16_hi v197, v163 offset:1008
	ds_write_b16 v207, v164
	ds_write_b16_d16_hi v207, v164 offset:144
	ds_write_b16 v207, v165 offset:288
	ds_write_b16_d16_hi v207, v165 offset:432
	ds_write_b16 v207, v166 offset:576
	ds_write_b16_d16_hi v207, v166 offset:720
	ds_write_b16 v207, v167 offset:864
	ds_write_b16_d16_hi v207, v167 offset:1008
	ds_write_b16 v227, v168
	ds_write_b16_d16_hi v227, v168 offset:144
	ds_write_b16 v227, v169 offset:288
	ds_write_b16_d16_hi v227, v169 offset:432
	ds_write_b16 v227, v170 offset:576
	ds_write_b16_d16_hi v227, v170 offset:720
	ds_write_b16 v227, v171 offset:864
	ds_write_b16_d16_hi v227, v171 offset:1008
	ds_write_b16 v237, v172
	ds_write_b16_d16_hi v237, v172 offset:144
	ds_write_b16 v237, v173 offset:288
	ds_write_b16_d16_hi v237, v173 offset:432
	ds_write_b16 v237, v174 offset:576
	ds_write_b16_d16_hi v237, v174 offset:720
	ds_write_b16 v237, v175 offset:864
	ds_write_b16_d16_hi v237, v175 offset:1008

; __device__ __forceinline__ int tidx() { int t = threadIdx.x; asm volatile("" : "+v"(t)); return t; }
; __device__ __forceinline__ void stage_rows128_norm(bf16_t* dst, const bf16_t* P, int r0, int rstride, int col, const float* __restrict__ gain, float qs) {
;     const int tid = tidx(), lane = tid & 63;
;     const f32x4 g0 = *(const f32x4*)(gain + (tid & 15) * 8), g1 = *(const f32x4*)(gain + (tid & 15) * 8 + 4);
; #pragma unroll
;     for (int i = 0; i < 4; ++i) {
;         const int idx = tid + 512 * i, r = idx >> 4, ch = idx & 15;
;         const u32x4 raw = *(const u32x4*)(P + pidx(r0 + r * rstride, col + ch * 8));
;         float v[8] = {bflo(raw[0]), bfhi(raw[0]), bflo(raw[1]), bfhi(raw[1]), bflo(raw[2]), bfhi(raw[2]), bflo(raw[3]), bfhi(raw[3])};
;         float ss = 0.f;
; #pragma unroll
;         for (int j = 0; j < 8; ++j) ss += v[j] * v[j];
;         ss += shx(ss, 1, lane); ss += shx(ss, 2, lane); ss += shx(ss, 4, lane); ss += shx(ss, 8, lane);
;         const float inv = rsqrtf(ss * (1.f / 128.f) + EPS) * qs;
; __device__ __forceinline__ void dil_item(const Params& p, int item, int l, unsigned char* lds) {
;     const int tid = tidx(), w = tid >> 6, lane = tid & 63, fr = lane & 15, fq = lane >> 4;
;     const bf16_t* P = (const bf16_t*)(p.ws + W_PROJ);
;     float* ODG = (float*)(p.ws + W_ODG); float* LSE = (float*)(p.ws + W_LSE);
;     const int g = item >> 7, rem = item & 127, hh = rem >> 6, s6 = rem & 63;
;     const int r = g == 0 ? 1 : (g == 1 ? 4 : 16), nb = 64 / r, rho = s6 / nb, n = s6 % nb;
;     const int head = 2 * g + hh;
;     const float slope = exp2f(-8.f * (float)(head + 1) / 6.f) * (float)r;
;     bf16_t* Qs = (bf16_t*)(lds + AT_Q);
;     const float* gq = p.in[9] + l * 128; const float* gk = p.in[10] + l * 128;
;     const f32x4 gk0 = *(const f32x4*)(gk + (tid & 15) * 8), gk1 = *(const f32x4*)(gk + (tid & 15) * 8 + 4);
;     const int kcol = C_KDIL + head * 128, vcol = C_VDIL + head * 128;
;     __syncthreads();
;     TileRegs tr;
;     int c = n == 0 ? 2 : 0;
;     tile_load(tr, P, (128 * (n - 1) + 64 * c) * r + rho, r, kcol, vcol, tid);
;     stage_rows128_norm(Qs, P, (128 * n) * r + rho, r, C_QDIL + head * 128, gq, 0.08838834764831845f);
;     tile_write(tr, lds + AT_BUF, gk0, gk1, tid, lane);
;     tile_load(tr, P, (128 * (n - 1) + 64 * (c + 1)) * r + rho, r, kcol, vcol, tid);
.LBB0_107:
	s_and_b64 vcc, exec, s[0:1]
	s_cbranch_vccz .LBB0_119
	s_add_i32 s0, s15, 0xfffffe80
	s_lshr_b32 s16, s0, 7
	s_bfe_u32 s5, s15, 0x10006
	s_and_b32 s1, s15, 63
	s_cmp_eq_u32 s16, 1
	s_cselect_b32 s4, 4, 16
	s_cselect_b32 s17, 2, 4
	s_cmpk_lt_u32 s0, 0x80
	s_cselect_b32 s17, 0, s17
	s_cselect_b32 s31, 1, s4
	s_lshr_b32 s0, 64, s17
	s_xor_b32 s4, s17, 6
	s_add_i32 s0, s0, -1
	s_lshr_b32 s18, s1, s4
	s_and_b32 s1, s0, s1
	s_lshl_b32 s0, s16, 1
	s_or_b32 s4, s0, s5
	s_not_b32 s0, s4
	s_lshl_b32 s19, s4, 7
	s_lshl_b32 s0, s0, 3
	s_add_i32 s30, s19, 0xf00
	s_cmp_eq_u32 s1, 0
	s_cselect_b32 s25, 2, 0
	v_mov_b32_e32 v39, v185
	s_lshl_b32 s19, s1, 7
	s_lshl_b32 s28, s25, 6
	s_add_i32 s1, s28, s19
	v_lshlrev_b32_e32 v0, 3, v39
	v_and_b32_e32 v85, 0x78, v0
	v_readlane_b32 s36, v245, 49
	s_add_i32 s33, s1, 0xffffff80
	v_lshlrev_b32_e32 v0, 2, v85
	v_readlane_b32 s37, v245, 50
	s_lshl_b32 s33, s33, s17
	s_waitcnt vmcnt(0)
	v_add_u32_e32 v20, 0x200, v39
	s_nop 1
	global_load_dwordx4 v[2:5], v0, s[36:37] offset:16
	global_load_dwordx4 v[6:9], v0, s[36:37]
	s_or_b32 s33, s33, s18
	s_lshl_b32 s36, s4, 21
	v_ashrrev_i32_e32 v52, 4, v20
	s_add_u32 s36, s2, s36
	v_lshlrev_b32_e32 v88, s17, v52
	s_addc_u32 s37, s3, 0
	v_lshlrev_b32_e32 v0, 1, v85
	v_add_u32_e32 v16, s33, v88
	v_and_b32_e32 v84, 63, v39
	v_lshl_add_u64 v[10:11], s[36:37], 0, v[0:1]
	s_mov_b64 s[38:39], 0x3000000
	v_ashrrev_i32_e32 v17, 31, v16
	s_waitcnt lgkmcnt(0)
	v_lshl_add_u64 v[74:75], v[10:11], 0, s[38:39]
	v_lshlrev_b32_e32 v86, s17, v84
	v_ashrrev_i32_e32 v67, 3, v39
	v_lshlrev_b64 v[16:17], 8, v[16:17]
	v_ashrrev_i32_e32 v68, 3, v20
	v_add_u32_e32 v10, s33, v86
	v_ashrrev_i32_e32 v66, 4, v39
	v_add_u32_e32 v14, s30, v67
	v_lshl_add_u64 v[18:19], v[74:75], 0, v[16:17]
	v_add_u32_e32 v16, s30, v68
	v_ashrrev_i32_e32 v11, 31, v10
	v_lshlrev_b32_e32 v87, s17, v66
	v_ashrrev_i32_e32 v14, 7, v14
	v_ashrrev_i32_e32 v16, 7, v16
	v_lshlrev_b64 v[10:11], 8, v[10:11]
	v_add_u32_e32 v12, s33, v87
	v_ashrrev_i32_e32 v15, 31, v14
	v_ashrrev_i32_e32 v17, 31, v16
	v_lshl_add_u64 v[10:11], s[2:3], 0, v[10:11]
	v_ashrrev_i32_e32 v13, 31, v12
	v_and_b32_e32 v38, 0x78, v67
	v_lshlrev_b64 v[76:77], 21, v[14:15]
	v_and_b32_e32 v40, 0x78, v68
	v_lshlrev_b64 v[78:79], 21, v[16:17]
	v_lshlrev_b64 v[12:13], 8, v[12:13]
	v_lshl_add_u64 v[14:15], v[10:11], 0, v[76:77]
	v_lshlrev_b32_e32 v42, 1, v38
	v_mov_b32_e32 v43, v1
	v_lshl_add_u64 v[10:11], v[10:11], 0, v[78:79]
	v_lshlrev_b32_e32 v44, 1, v40
	v_mov_b32_e32 v45, v1
	v_lshl_add_u64 v[12:13], v[74:75], 0, v[12:13]
	v_lshl_add_u64 v[14:15], v[14:15], 0, v[42:43]
	v_lshl_add_u64 v[10:11], v[10:11], 0, v[44:45]
	v_mov_b32_e32 v53, v185
	s_waitcnt lgkmcnt(0)
	s_barrier
	flat_load_dwordx4 v[30:33], v[12:13]
	s_nop 0
	flat_load_dwordx4 v[14:17], v[14:15]
	s_nop 0
	flat_load_dwordx4 v[26:29], v[18:19]
	s_nop 0
	flat_load_dwordx4 v[10:13], v[10:11]
	v_mov_b32_e32 v47, v1
	v_lshlrev_b32_e32 v18, 3, v53
	v_and_b32_e32 v20, 0x78, v18
	v_lshlrev_b32_e32 v46, 1, v20
	s_lshl_b32 s30, s19, s17
	v_lshl_add_u64 v[18:19], s[36:37], 0, v[46:47]
	s_mov_b64 s[36:37], 0x2400000
	v_ashrrev_i32_e32 v64, 4, v53
	s_or_b32 s30, s30, s18
	v_lshl_add_u64 v[48:49], v[18:19], 0, s[36:37]
	v_lshlrev_b32_e32 v18, s17, v64
	v_add_u32_e32 v18, s30, v18
	v_ashrrev_i32_e32 v19, 31, v18
	v_lshlrev_b64 v[18:19], 8, v[18:19]
	v_lshl_add_u64 v[18:19], v[48:49], 0, v[18:19]
	flat_load_dwordx4 v[34:37], v[18:19]
	s_lshl_b32 s36, 0x2000, s17
	s_mov_b32 s37, 0
	v_lshl_add_u64 v[152:153], v[18:19], 0, s[36:37]
	flat_load_dwordx4 v[156:159], v[152:153]
	v_lshl_add_u64 v[152:153], v[152:153], 0, s[36:37]
	flat_load_dwordx4 v[160:163], v[152:153]
	v_lshl_add_u64 v[152:153], v[152:153], 0, s[36:37]
	flat_load_dwordx4 v[164:167], v[152:153]
	v_readlane_b32 s36, v245, 47
	v_lshlrev_b32_e32 v18, 2, v20
	v_readlane_b32 s37, v245, 48
	s_nop 4
	global_load_dwordx4 v[22:25], v18, s[36:37]
	s_nop 0
	global_load_dwordx4 v[18:21], v18, s[36:37] offset:16
	v_lshlrev_b32_e32 v47, 2, v53
	v_bitop3_b32 v41, v47, 4, v211 bitop3:0x6c
	v_add_u32_e32 v46, 0, v46
	s_movk_i32 s38, 0x110
	s_movk_i32 s33, 0x88
	v_mul_lo_u32 v90, v66, s33
	v_mul_lo_u32 v96, v52, s33
	v_add_u32_e32 v0, 0, v0
	v_lshl_add_u32 v100, v90, 1, v0
	v_lshl_add_u32 v102, v96, 1, v0
	v_add_u32_e32 v0, 0x600, v53
	v_ashrrev_i32_e32 v98, 4, v0
	v_cvt_f32_i32_e32 v101, s0
	s_sub_i32 s0, s1, 64
	s_lshl_b32 s0, s0, s17
	s_or_b32 s33, s0, s18
	v_lshlrev_b32_e32 v89, 2, v84
	v_xor_b32_e32 v91, 4, v89
	v_xor_b32_e32 v92, 8, v89
	v_xor_b32_e32 v93, 16, v89
	v_xor_b32_e32 v94, 32, v89
	s_mov_b32 s39, 0x40c00000
	v_and_b32_e32 v80, 15, v39
	v_mov_b32_e32 v108, 0
	v_mul_u32_u24_e32 v106, 0x110, v80
	s_waitcnt vmcnt(0) lgkmcnt(0)
	v_lshlrev_b32_e32 v66, 16, v28
	v_lshlrev_b32_e32 v62, 16, v34
	v_and_b32_e32 v63, 0xffff0000, v34
	v_lshlrev_b32_e32 v58, 16, v35
	v_and_b32_e32 v59, 0xffff0000, v35
	v_pk_mul_f32 v[34:35], v[62:63], v[62:63]
	v_pk_mul_f32 v[60:61], v[58:59], v[58:59]
	v_add_f32_e32 v34, v34, v35
	v_lshlrev_b32_e32 v56, 16, v36
	v_and_b32_e32 v57, 0xffff0000, v36
	v_add_f32_e32 v34, v60, v34
	v_lshlrev_b32_e32 v54, 16, v37
	v_and_b32_e32 v55, 0xffff0000, v37
	v_pk_mul_f32 v[36:37], v[56:57], v[56:57]
	v_add_f32_e32 v34, v61, v34
	v_add_f32_e32 v34, v36, v34
	v_pk_mul_f32 v[50:51], v[54:55], v[54:55]
	v_add_f32_e32 v34, v37, v34
	v_add_f32_e32 v34, v50, v34
	v_add_f32_e32 v34, v51, v34
	ds_bpermute_b32 v35, v41, v34
	v_bitop3_b32 v51, v47, 8, v211 bitop3:0x6c
	v_bitop3_b32 v50, v47, 16, v211 bitop3:0x6c
	v_bitop3_b32 v47, v47, 32, v211 bitop3:0x6c
	s_waitcnt lgkmcnt(0)
	v_add_f32_e32 v34, v34, v35
	ds_bpermute_b32 v35, v51, v34
	s_waitcnt lgkmcnt(0)
; __device__ __forceinline__ unsigned pk2(float lo, float hi) { const f32v2_t v = {lo, hi}; return __builtin_bit_cast(unsigned, __builtin_convertvector(v, bf16v2_t)); }
; __device__ __forceinline__ int tidx() { int t = threadIdx.x; asm volatile("" : "+v"(t)); return t; }
; __device__ __forceinline__ float shx(float v, int mask, int lane) { return __int_as_float(__builtin_amdgcn_ds_bpermute((lane ^ mask) << 2, __float_as_int(v))); }
; __device__ __forceinline__ size_t pidx(int row, int col) { return (size_t)(col >> 7) * ((size_t)T * 128) + (size_t)row * 128 + (col & 127); }
; __device__ __forceinline__ float bflo(unsigned u) { return __uint_as_float(u << 16); }
; __device__ __forceinline__ float bfhi(unsigned u) { return __uint_as_float(u & 0xffff0000u); }
; __device__ __forceinline__ void stage_rows128_norm(bf16_t* dst, const bf16_t* P, int r0, int rstride, int col, const float* __restrict__ gain, float qs) {
;     const int tid = tidx(), lane = tid & 63;
;     const f32x4 g0 = *(const f32x4*)(gain + (tid & 15) * 8), g1 = *(const f32x4*)(gain + (tid & 15) * 8 + 4);
; #pragma unroll
;     for (int i = 0; i < 4; ++i) {
;         const int idx = tid + 512 * i, r = idx >> 4, ch = idx & 15;
;         const u32x4 raw = *(const u32x4*)(P + pidx(r0 + r * rstride, col + ch * 8));
;         float v[8] = {bflo(raw[0]), bfhi(raw[0]), bflo(raw[1]), bfhi(raw[1]), bflo(raw[2]), bfhi(raw[2]), bflo(raw[3]), bfhi(raw[3])};
;         float ss = 0.f;
; #pragma unroll
;         for (int j = 0; j < 8; ++j) ss += v[j] * v[j];
;         ss += shx(ss, 1, lane); ss += shx(ss, 2, lane); ss += shx(ss, 4, lane); ss += shx(ss, 8, lane);
;         const float inv = rsqrtf(ss * (1.f / 128.f) + EPS) * qs;
;         u32x4 o = {pk2(v[0] * inv * g0[0], v[1] * inv * g0[1]), pk2(v[2] * inv * g0[2], v[3] * inv * g0[3]),
;                    pk2(v[4] * inv * g1[0], v[5] * inv * g1[1]), pk2(v[6] * inv * g1[2], v[7] * inv * g1[3])};
;         *(u32x4*)(dst + r * 136 + ch * 8) = o;
;     }
; }
	v_add_f32_e32 v34, v34, v35
	ds_bpermute_b32 v35, v50, v34
	s_waitcnt lgkmcnt(0)
	v_add_f32_e32 v34, v34, v35
	ds_bpermute_b32 v35, v47, v34
	s_waitcnt lgkmcnt(0)
	v_add_f32_e32 v34, v34, v35
	v_fmamk_f32 v34, v34, 0x3c000000, v184
	v_mul_f32_e32 v35, 0x4b800000, v34
	v_cmp_gt_f32_e32 vcc, s90, v34
	s_nop 1
	v_cndmask_b32_e32 v34, v34, v35, vcc
	v_rsq_f32_e32 v34, v34
	s_nop 0
	v_mul_f32_e32 v35, 0x45800000, v34
	v_cndmask_b32_e32 v34, v34, v35, vcc
	v_mul_f32_e32 v60, 0x3db504f3, v34
	v_pk_mul_f32 v[34:35], v[60:61], v[62:63] op_sel_hi:[0,1]
	v_pk_mul_f32 v[36:37], v[60:61], v[58:59] op_sel_hi:[0,1]
	v_pk_mul_f32 v[34:35], v[22:23], v[34:35]
	v_pk_mul_f32 v[36:37], v[24:25], v[36:37]
	v_cvt_pk_bf16_f32 v34, v34, v35
	v_cvt_pk_bf16_f32 v35, v36, v37
	v_pk_mul_f32 v[36:37], v[60:61], v[56:57] op_sel_hi:[0,1]
	v_pk_mul_f32 v[54:55], v[60:61], v[54:55] op_sel_hi:[0,1]
	v_pk_mul_f32 v[36:37], v[18:19], v[36:37]
	v_pk_mul_f32 v[54:55], v[20:21], v[54:55]
	v_cvt_pk_bf16_f32 v36, v36, v37
	v_cvt_pk_bf16_f32 v37, v54, v55
	v_mad_u64_u32 v[54:55], s[36:37], v64, s38, v[46:47]
	ds_write_b128 v54, v[34:37]
	v_add_u32_e32 v34, 0x200, v53
	v_ashrrev_i32_e32 v69, 4, v34
	v_lshlrev_b32_e32 v34, s17, v69
	v_add_u32_e32 v34, s30, v34
	v_ashrrev_i32_e32 v35, 31, v34
	v_lshlrev_b64 v[34:35], 8, v[34:35]
	v_lshl_add_u64 v[34:35], v[48:49], 0, v[34:35]
	v_mov_b64_e32 v[34:35], v[156:157]
	v_mov_b64_e32 v[36:37], v[158:159]
	s_waitcnt lgkmcnt(0)
	v_lshlrev_b32_e32 v58, 16, v34
	v_and_b32_e32 v59, 0xffff0000, v34
	v_lshlrev_b32_e32 v54, 16, v37
	v_and_b32_e32 v55, 0xffff0000, v37
	v_lshlrev_b32_e32 v56, 16, v36
	v_and_b32_e32 v57, 0xffff0000, v36
	v_lshlrev_b32_e32 v36, 16, v35
	v_and_b32_e32 v37, 0xffff0000, v35
	v_pk_mul_f32 v[64:65], v[58:59], v[58:59]
	v_pk_mul_f32 v[62:63], v[36:37], v[36:37]
	v_add_f32_e32 v64, v64, v65
	v_add_f32_e32 v62, v62, v64
	v_pk_mul_f32 v[60:61], v[56:57], v[56:57]
	v_add_f32_e32 v62, v63, v62
	v_add_f32_e32 v60, v60, v62
	v_pk_mul_f32 v[34:35], v[54:55], v[54:55]
	v_add_f32_e32 v60, v61, v60
	v_add_f32_e32 v34, v34, v60
	v_add_f32_e32 v34, v35, v34
	ds_bpermute_b32 v35, v41, v34
	v_add_u32_e32 v60, 0x400, v53
	v_ashrrev_i32_e32 v64, 4, v60
	v_mad_u64_u32 v[60:61], s[36:37], v69, s38, v[46:47]
	s_waitcnt lgkmcnt(0)
	v_add_f32_e32 v34, v34, v35
	ds_bpermute_b32 v35, v51, v34
	s_movk_i32 s36, 0x48
	v_and_b32_e32 v65, 0xffff0000, v29
	s_waitcnt lgkmcnt(0)
	v_add_f32_e32 v34, v34, v35
	ds_bpermute_b32 v35, v50, v34
	s_waitcnt lgkmcnt(0)
	v_add_f32_e32 v35, v34, v35
	ds_bpermute_b32 v62, v47, v35
	v_lshlrev_b32_e32 v34, s17, v64
	v_add_u32_e32 v34, s30, v34
	s_waitcnt lgkmcnt(0)
	v_add_f32_e32 v35, v35, v62
	v_fmamk_f32 v35, v35, 0x3c000000, v184
	v_mul_f32_e32 v61, 0x4b800000, v35
	v_cmp_gt_f32_e32 vcc, s90, v35
	s_nop 1
	v_cndmask_b32_e32 v35, v35, v61, vcc
	v_rsq_f32_e32 v61, v35
	v_ashrrev_i32_e32 v35, 31, v34
	v_lshlrev_b64 v[34:35], 8, v[34:35]
	v_lshl_add_u64 v[62:63], v[48:49], 0, v[34:35]
	v_mul_f32_e32 v34, 0x45800000, v61
	v_cndmask_b32_e32 v34, v61, v34, vcc
	v_mul_f32_e32 v34, 0x3db504f3, v34
	v_pk_mul_f32 v[58:59], v[34:35], v[58:59] op_sel_hi:[0,1]
	v_pk_mul_f32 v[36:37], v[34:35], v[36:37] op_sel_hi:[0,1]
	v_pk_mul_f32 v[56:57], v[34:35], v[56:57] op_sel_hi:[0,1]
	v_pk_mul_f32 v[34:35], v[34:35], v[54:55] op_sel_hi:[0,1]
	v_pk_mul_f32 v[54:55], v[22:23], v[58:59]
	v_pk_mul_f32 v[36:37], v[24:25], v[36:37]
	v_pk_mul_f32 v[56:57], v[18:19], v[56:57]
	v_pk_mul_f32 v[58:59], v[20:21], v[34:35]
	v_cvt_pk_bf16_f32 v34, v54, v55
	v_cvt_pk_bf16_f32 v35, v36, v37
	v_cvt_pk_bf16_f32 v36, v56, v57
	v_cvt_pk_bf16_f32 v37, v58, v59
	ds_write_b128 v60, v[34:37]
	v_mov_b64_e32 v[34:35], v[160:161]
	v_mov_b64_e32 v[36:37], v[162:163]
	v_and_b32_e32 v54, 0x1ffffff8, v67
	v_and_b32_e32 v56, 0x1ffffff8, v68
	v_lshl_add_u32 v55, v84, 1, 0
	v_mul_lo_u32 v95, v54, s36
	v_mul_lo_u32 v97, v56, s36
	v_lshl_add_u32 v81, v95, 1, v55
	v_lshl_add_u32 v103, v97, 1, v55
	v_and_b32_e32 v67, 0xffff0000, v28
	v_div_scale_f32 v104, s[36:37], s39, s39, v101
	v_rcp_f32_e32 v105, v104
	s_waitcnt lgkmcnt(0)
	v_lshlrev_b32_e32 v56, 16, v34
	v_and_b32_e32 v57, 0xffff0000, v34
	v_lshlrev_b32_e32 v52, 16, v37
	v_and_b32_e32 v53, 0xffff0000, v37
	v_lshlrev_b32_e32 v54, 16, v36
	v_and_b32_e32 v55, 0xffff0000, v36
	v_lshlrev_b32_e32 v36, 16, v35
	v_and_b32_e32 v37, 0xffff0000, v35
	v_pk_mul_f32 v[62:63], v[56:57], v[56:57]
	v_pk_mul_f32 v[60:61], v[36:37], v[36:37]
	v_add_f32_e32 v0, v62, v63
	v_add_f32_e32 v0, v60, v0
	v_pk_mul_f32 v[58:59], v[54:55], v[54:55]
	v_add_f32_e32 v0, v61, v0
	v_add_f32_e32 v0, v58, v0
	v_pk_mul_f32 v[34:35], v[52:53], v[52:53]
	v_add_f32_e32 v0, v59, v0
	v_add_f32_e32 v0, v34, v0
	v_add_f32_e32 v0, v35, v0
	ds_bpermute_b32 v35, v41, v0
	v_mad_u64_u32 v[58:59], s[0:1], v64, s38, v[46:47]
	v_lshlrev_b32_e32 v62, 16, v30
	v_and_b32_e32 v63, 0xffff0000, v30
	s_waitcnt lgkmcnt(0)
	v_add_f32_e32 v0, v0, v35
	ds_bpermute_b32 v59, v51, v0
	v_lshlrev_b32_e32 v34, s17, v98
	v_add_u32_e32 v34, s30, v34
	v_ashrrev_i32_e32 v35, 31, v34
	v_lshlrev_b64 v[34:35], 8, v[34:35]
	s_waitcnt lgkmcnt(0)
	v_add_f32_e32 v0, v0, v59
	ds_bpermute_b32 v59, v50, v0
	v_lshl_add_u64 v[34:35], v[48:49], 0, v[34:35]
	v_lshlrev_b32_e32 v48, 16, v33
	v_and_b32_e32 v49, 0xffff0000, v33
	v_lshlrev_b32_e32 v60, 16, v32
	s_waitcnt lgkmcnt(0)
	v_add_f32_e32 v0, v0, v59
	ds_bpermute_b32 v59, v47, v0
	v_and_b32_e32 v61, 0xffff0000, v32
	v_lshlrev_b32_e32 v32, 16, v31
	v_and_b32_e32 v33, 0xffff0000, v31
	v_lshlrev_b32_e32 v64, 16, v29
	s_waitcnt lgkmcnt(0)
; __device__ __forceinline__ unsigned pk2(float lo, float hi) { const f32v2_t v = {lo, hi}; return __builtin_bit_cast(unsigned, __builtin_convertvector(v, bf16v2_t)); }
; __device__ __forceinline__ float shx(float v, int mask, int lane) { return __int_as_float(__builtin_amdgcn_ds_bpermute((lane ^ mask) << 2, __float_as_int(v))); }
; __device__ __forceinline__ void stage_rows128_norm(bf16_t* dst, const bf16_t* P, int r0, int rstride, int col, const float* __restrict__ gain, float qs) {
;     ...
;         const int idx = tid + 512 * i, r = idx >> 4, ch = idx & 15;
;         const u32x4 raw = *(const u32x4*)(P + pidx(r0 + r * rstride, col + ch * 8));
;         float v[8] = {bflo(raw[0]), bfhi(raw[0]), bflo(raw[1]), bfhi(raw[1]), bflo(raw[2]), bfhi(raw[2]), bflo(raw[3]), bfhi(raw[3])};
;         float ss = 0.f;
; #pragma unroll
;         for (int j = 0; j < 8; ++j) ss += v[j] * v[j];
;         ss += shx(ss, 1, lane); ss += shx(ss, 2, lane); ss += shx(ss, 4, lane); ss += shx(ss, 8, lane);
;         const float inv = rsqrtf(ss * (1.f / 128.f) + EPS) * qs;
;         u32x4 o = {pk2(v[0] * inv * g0[0], v[1] * inv * g0[1]), pk2(v[2] * inv * g0[2], v[3] * inv * g0[3]),
;                    pk2(v[4] * inv * g1[0], v[5] * inv * g1[1]), pk2(v[6] * inv * g1[2], v[7] * inv * g1[3])};
;         *(u32x4*)(dst + r * 136 + ch * 8) = o;
;     }
; }
; __device__ __forceinline__ void tile_write(const TileRegs& t, unsigned char* buf, const f32x4& g0, const f32x4& g1, int tid, int lane) {
;     bf16_t* Ks = (bf16_t*)buf; bf16_t* VT = (bf16_t*)(buf + AT_VOFF);
; #pragma unroll
;     for (int i = 0; i < 2; ++i) {
;         const int idx = tid + 512 * i, r = idx >> 4, ch = idx & 15;
;         const u32x4 raw = t.k[i];
;         float v[8] = {bflo(raw[0]), bfhi(raw[0]), bflo(raw[1]), bfhi(raw[1]), bflo(raw[2]), bfhi(raw[2]), bflo(raw[3]), bfhi(raw[3])};
;         float ss = 0.f;
; #pragma unroll
;         for (int j = 0; j < 8; ++j) ss += v[j] * v[j];
;         ss += shx(ss, 1, lane); ss += shx(ss, 2, lane); ss += shx(ss, 4, lane); ss += shx(ss, 8, lane);
;         const float inv = rsqrtf(ss * (1.f / 128.f) + EPS);
;         u32x4 o = {pk2(v[0] * inv * g0[0], v[1] * inv * g0[1]), pk2(v[2] * inv * g0[2], v[3] * inv * g0[3]),
;                    pk2(v[4] * inv * g1[0], v[5] * inv * g1[1]), pk2(v[6] * inv * g1[2], v[7] * inv * g1[3])};
;         *(u32x4*)(Ks + r * 136 + ch * 8) = o;
	v_add_f32_e32 v0, v0, v59
	v_fmamk_f32 v0, v0, 0x3c000000, v184
	v_mul_f32_e32 v30, 0x4b800000, v0
	v_cmp_gt_f32_e32 vcc, s90, v0
	v_mov_b32_e32 v73, v63
	v_mov_b32_e32 v71, v62
	v_cndmask_b32_e32 v0, v0, v30, vcc
	v_rsq_f32_e32 v0, v0
	s_brev_b32 s0, 60
	s_mov_b32 s30, 0
	v_mul_f32_e32 v28, 0x45800000, v0
	v_cndmask_b32_e32 v0, v0, v28, vcc
	v_mul_f32_e32 v0, 0x3db504f3, v0
	v_pk_mul_f32 v[28:29], v[0:1], v[56:57] op_sel_hi:[0,1]
	v_pk_mul_f32 v[30:31], v[0:1], v[36:37] op_sel_hi:[0,1]
	v_pk_mul_f32 v[36:37], v[0:1], v[54:55] op_sel_hi:[0,1]
	v_pk_mul_f32 v[52:53], v[0:1], v[52:53] op_sel_hi:[0,1]
	v_pk_mul_f32 v[28:29], v[22:23], v[28:29]
	v_pk_mul_f32 v[30:31], v[24:25], v[30:31]
	v_pk_mul_f32 v[36:37], v[18:19], v[36:37]
	v_pk_mul_f32 v[52:53], v[20:21], v[52:53]
	v_cvt_pk_bf16_f32 v28, v28, v29
	v_cvt_pk_bf16_f32 v29, v30, v31
	v_cvt_pk_bf16_f32 v30, v36, v37
	v_cvt_pk_bf16_f32 v31, v52, v53
	ds_write_b128 v58, v[28:31]
	v_mov_b64_e32 v[28:29], v[164:165]
	v_mov_b64_e32 v[30:31], v[166:167]
	v_and_b32_e32 v37, 0xffff0000, v26
	v_lshlrev_b32_e32 v34, 16, v27
	v_and_b32_e32 v35, 0xffff0000, v27
	v_lshlrev_b32_e32 v36, 16, v26
	v_mov_b32_e32 v72, v37
	v_pk_mul_f32 v[26:27], v[48:49], v[48:49]
	v_pk_mul_f32 v[52:53], v[60:61], v[60:61]
	v_pk_mul_f32 v[54:55], v[32:33], v[32:33]
	v_pk_mul_f32 v[56:57], v[64:65], v[64:65]
	v_pk_mul_f32 v[58:59], v[66:67], v[66:67]
	v_pk_mul_f32 v[68:69], v[34:35], v[34:35]
	v_mov_b32_e32 v70, v36
	v_pk_mul_f32 v[72:73], v[72:73], v[72:73]
	v_mov_b32_e32 v82, v68
	v_mov_b32_e32 v83, v54
	v_mov_b32_e32 v54, v69
	v_mov_b32_e32 v68, v58
	v_mov_b32_e32 v69, v52
	v_mov_b32_e32 v52, v59
	v_mov_b32_e32 v58, v56
	v_mov_b32_e32 v59, v26
	v_mov_b32_e32 v26, v57
	v_pk_fma_f32 v[56:57], v[70:71], v[70:71], v[72:73]
	s_waitcnt lgkmcnt(0)
	v_lshlrev_b32_e32 v72, 16, v28
	v_pk_add_f32 v[56:57], v[82:83], v[56:57]
	v_and_b32_e32 v73, 0xffff0000, v28
	v_pk_add_f32 v[54:55], v[54:55], v[56:57]
	v_add_u32_e32 v56, s33, v87
	v_pk_add_f32 v[54:55], v[68:69], v[54:55]
	v_ashrrev_i32_e32 v57, 31, v56
	v_pk_add_f32 v[52:53], v[52:53], v[54:55]
	v_add_u32_e32 v54, s33, v86
	v_pk_add_f32 v[52:53], v[58:59], v[52:53]
	v_ashrrev_i32_e32 v55, 31, v54
	v_pk_add_f32 v[26:27], v[26:27], v[52:53]
	ds_bpermute_b32 v53, v91, v27
	ds_bpermute_b32 v52, v91, v26
	v_lshlrev_b64 v[54:55], 8, v[54:55]
	v_lshl_add_u64 v[54:55], s[2:3], 0, v[54:55]
	v_lshl_add_u64 v[68:69], v[54:55], 0, v[76:77]
	v_lshl_add_u64 v[54:55], v[54:55], 0, v[78:79]
	s_waitcnt lgkmcnt(0)
	v_pk_add_f32 v[26:27], v[26:27], v[52:53]
	ds_bpermute_b32 v53, v92, v27
	ds_bpermute_b32 v52, v92, v26
	v_lshl_add_u64 v[68:69], v[68:69], 0, v[42:43]
	v_lshl_add_u64 v[70:71], v[54:55], 0, v[44:45]
	v_lshlrev_b32_e32 v54, 16, v31
	v_and_b32_e32 v55, 0xffff0000, v31
	s_waitcnt lgkmcnt(0)
	v_pk_add_f32 v[26:27], v[26:27], v[52:53]
	ds_bpermute_b32 v53, v93, v27
	ds_bpermute_b32 v52, v93, v26
	v_add_u32_e32 v58, s33, v88
	v_ashrrev_i32_e32 v59, 31, v58
	v_lshlrev_b64 v[56:57], 8, v[56:57]
	v_lshlrev_b64 v[58:59], 8, v[58:59]
	s_waitcnt lgkmcnt(0)
	v_pk_add_f32 v[26:27], v[26:27], v[52:53]
	ds_bpermute_b32 v53, v94, v27
	ds_bpermute_b32 v52, v94, v26
	v_lshl_add_u64 v[56:57], v[74:75], 0, v[56:57]
	v_lshl_add_u64 v[58:59], v[74:75], 0, v[58:59]
	s_movk_i32 s33, 0x800
	s_waitcnt lgkmcnt(0)
	v_pk_add_f32 v[26:27], v[26:27], v[52:53]
	s_nop 0
	v_pk_fma_f32 v[26:27], v[26:27], s[0:1], v[184:185] op_sel_hi:[1,0,0]
	s_nop 0
	v_mul_f32_e32 v0, 0x4b800000, v27
	v_cmp_gt_f32_e32 vcc, s90, v27
	v_mul_f32_e32 v42, 0x4b800000, v26
	v_cmp_gt_f32_e64 s[0:1], s90, v26
	v_cndmask_b32_e32 v0, v27, v0, vcc
	v_rsq_f32_e32 v0, v0
	v_cndmask_b32_e64 v26, v26, v42, s[0:1]
	v_mad_u64_u32 v[42:43], s[36:37], v98, s38, v[46:47]
	v_mul_f32_e32 v27, 0x45800000, v0
	v_cndmask_b32_e32 v0, v0, v27, vcc
	v_pk_mul_f32 v[44:45], v[0:1], v[62:63] op_sel_hi:[0,1]
	v_lshlrev_b32_e32 v62, 16, v29
	v_and_b32_e32 v63, 0xffff0000, v29
	v_pk_mul_f32 v[98:99], v[72:73], v[72:73]
	v_pk_mul_f32 v[32:33], v[0:1], v[32:33] op_sel_hi:[0,1]
	v_pk_mul_f32 v[52:53], v[0:1], v[60:61] op_sel_hi:[0,1]
	v_pk_mul_f32 v[48:49], v[0:1], v[48:49] op_sel_hi:[0,1]
	v_pk_mul_f32 v[82:83], v[62:63], v[62:63]
	v_add_f32_e32 v0, v98, v99
	v_lshlrev_b32_e32 v60, 16, v30
	v_and_b32_e32 v61, 0xffff0000, v30
	v_add_f32_e32 v0, v82, v0
	v_pk_mul_f32 v[30:31], v[60:61], v[60:61]
	v_add_f32_e32 v0, v83, v0
	v_add_f32_e32 v0, v30, v0
	v_pk_mul_f32 v[28:29], v[54:55], v[54:55]
	v_add_f32_e32 v0, v31, v0
	v_add_f32_e32 v0, v28, v0
	v_add_f32_e32 v0, v29, v0
	ds_bpermute_b32 v41, v41, v0
	v_rsq_f32_e32 v26, v26
	v_pk_mul_f32 v[32:33], v[8:9], v[32:33]
	v_pk_mul_f32 v[48:49], v[4:5], v[48:49]
	v_bfe_u32 v98, v39, 4, 2
	s_waitcnt lgkmcnt(0)
; __device__ __forceinline__ void tile_write(const TileRegs& t, unsigned char* buf, const f32x4& g0, const f32x4& g1, int tid, int lane) {
;     bf16_t* Ks = (bf16_t*)buf; bf16_t* VT = (bf16_t*)(buf + AT_VOFF);
; #pragma unroll
;     for (int i = 0; i < 2; ++i) {
;         const int idx = tid + 512 * i, r = idx >> 4, ch = idx & 15;
;         const u32x4 raw = t.k[i];
;         float v[8] = {bflo(raw[0]), bfhi(raw[0]), bflo(raw[1]), bfhi(raw[1]), bflo(raw[2]), bfhi(raw[2]), bflo(raw[3]), bfhi(raw[3])};
;         float ss = 0.f;
; #pragma unroll
;         for (int j = 0; j < 8; ++j) ss += v[j] * v[j];
;         ss += shx(ss, 1, lane); ss += shx(ss, 2, lane); ss += shx(ss, 4, lane); ss += shx(ss, 8, lane);
;         const float inv = rsqrtf(ss * (1.f / 128.f) + EPS);
;         u32x4 o = {pk2(v[0] * inv * g0[0], v[1] * inv * g0[1]), pk2(v[2] * inv * g0[2], v[3] * inv * g0[3]),
;                    pk2(v[4] * inv * g1[0], v[5] * inv * g1[1]), pk2(v[6] * inv * g1[2], v[7] * inv * g1[3])};
;         *(u32x4*)(Ks + r * 136 + ch * 8) = o;
;         const u32x4 rv = t.v[i];
;         bf16_t* d = VT + ((idx >> 6) * 8) * 72 + (idx & 63);
;         d[0] = (bf16_t)(rv[0] & 0xffff); d[72] = (bf16_t)(rv[0] >> 16); d[144] = (bf16_t)(rv[1] & 0xffff); d[216] = (bf16_t)(rv[1] >> 16);
;         d[288] = (bf16_t)(rv[2] & 0xffff); d[360] = (bf16_t)(rv[2] >> 16); d[432] = (bf16_t)(rv[3] & 0xffff); d[504] = (bf16_t)(rv[3] >> 16);
;     }
; }
; __device__ __forceinline__ void dil_item(const Params& p, int item, int l, unsigned char* lds) {
;     ...
;     const float slope = exp2f(-8.f * (float)(head + 1) / 6.f) * (float)r;
;     bf16_t* Qs = (bf16_t*)(lds + AT_Q);
;     const float* gq = p.in[9] + l * 128; const float* gk = p.in[10] + l * 128;
;     const f32x4 gk0 = *(const f32x4*)(gk + (tid & 15) * 8), gk1 = *(const f32x4*)(gk + (tid & 15) * 8 + 4);
;     const int kcol = C_KDIL + head * 128, vcol = C_VDIL + head * 128;
;     __syncthreads();
;     TileRegs tr;
;     int c = n == 0 ? 2 : 0;
;     tile_load(tr, P, (128 * (n - 1) + 64 * c) * r + rho, r, kcol, vcol, tid);
;     stage_rows128_norm(Qs, P, (128 * n) * r + rho, r, C_QDIL + head * 128, gq, 0.08838834764831845f);
;     tile_write(tr, lds + AT_BUF, gk0, gk1, tid, lane);
;     tile_load(tr, P, (128 * (n - 1) + 64 * (c + 1)) * r + rho, r, kcol, vcol, tid);
;     __syncthreads();
;     bf16x8 qf[4];
; #pragma unroll
	v_add_f32_e32 v0, v0, v41
	ds_bpermute_b32 v41, v51, v0
	v_mul_f32_e32 v43, 0x45800000, v26
	v_cndmask_b32_e64 v26, v26, v43, s[0:1]
	v_pk_mul_f32 v[30:31], v[26:27], v[66:67] op_sel_hi:[0,1]
	v_pk_mul_f32 v[28:29], v[26:27], v[34:35] op_sel_hi:[0,1]
	s_waitcnt lgkmcnt(0)
	v_add_f32_e32 v0, v0, v41
	ds_bpermute_b32 v41, v50, v0
	v_pk_mul_f32 v[34:35], v[6:7], v[44:45]
	v_pk_mul_f32 v[44:45], v[2:3], v[52:53]
	v_pk_mul_f32 v[52:53], v[2:3], v[30:31]
	v_pk_mul_f32 v[36:37], v[26:27], v[36:37] op_sel_hi:[0,1]
	s_waitcnt lgkmcnt(0)
	v_add_f32_e32 v0, v0, v41
	ds_bpermute_b32 v31, v47, v0
	v_pk_mul_f32 v[26:27], v[26:27], v[64:65] op_sel_hi:[0,1]
	v_pk_mul_f32 v[64:65], v[4:5], v[26:27]
	v_cvt_pk_bf16_f32 v26, v34, v35
	v_pk_mul_f32 v[36:37], v[6:7], v[36:37]
	s_waitcnt lgkmcnt(0)
	v_add_f32_e32 v0, v0, v31
	v_fmamk_f32 v0, v0, 0x3c000000, v184
	v_mul_f32_e32 v31, 0x4b800000, v0
	v_cmp_gt_f32_e32 vcc, s90, v0
	v_pk_mul_f32 v[50:51], v[8:9], v[28:29]
	v_cvt_pk_bf16_f32 v28, v44, v45
	v_cndmask_b32_e32 v0, v0, v31, vcc
	v_rsq_f32_e32 v0, v0
	v_cvt_pk_bf16_f32 v30, v36, v37
	v_cvt_pk_bf16_f32 v27, v32, v33
	v_cvt_pk_bf16_f32 v29, v48, v49
	v_mul_f32_e32 v34, 0x45800000, v0
	v_cndmask_b32_e32 v0, v0, v34, vcc
	v_mul_f32_e32 v0, 0x3db504f3, v0
	v_pk_mul_f32 v[34:35], v[0:1], v[72:73] op_sel_hi:[0,1]
	v_pk_mul_f32 v[36:37], v[0:1], v[62:63] op_sel_hi:[0,1]
	v_pk_mul_f32 v[44:45], v[0:1], v[60:61] op_sel_hi:[0,1]
	v_pk_mul_f32 v[46:47], v[0:1], v[54:55] op_sel_hi:[0,1]
	v_pk_mul_f32 v[22:23], v[22:23], v[34:35]
	v_pk_mul_f32 v[24:25], v[24:25], v[36:37]
	v_pk_mul_f32 v[34:35], v[18:19], v[44:45]
	v_pk_mul_f32 v[36:37], v[20:21], v[46:47]
	v_cvt_pk_bf16_f32 v18, v22, v23
	v_cvt_pk_bf16_f32 v19, v24, v25
	v_cvt_pk_bf16_f32 v20, v34, v35
	v_cvt_pk_bf16_f32 v21, v36, v37
	v_cvt_pk_bf16_f32 v31, v50, v51
	v_cvt_pk_bf16_f32 v32, v52, v53
	v_cvt_pk_bf16_f32 v33, v64, v65
	ds_write_b128 v42, v[18:21]
	ds_write_b128 v100, v[26:29] offset:34816
	ds_write_b16 v81, v14 offset:52224
	ds_write_b16_d16_hi v81, v14 offset:52368
	ds_write_b16 v81, v15 offset:52512
	ds_write_b16_d16_hi v81, v15 offset:52656
	ds_write_b16 v81, v16 offset:52800
	ds_write_b16_d16_hi v81, v16 offset:52944
	ds_write_b16 v81, v17 offset:53088
	ds_write_b16_d16_hi v81, v17 offset:53232
	ds_write_b128 v102, v[30:33] offset:34816
	ds_write_b16 v103, v10 offset:52224
	ds_write_b16_d16_hi v103, v10 offset:52368
	ds_write_b16 v103, v11 offset:52512
	ds_write_b16_d16_hi v103, v11 offset:52656
	ds_write_b16 v103, v12 offset:52800
	ds_write_b16_d16_hi v103, v12 offset:52944
	ds_write_b16 v103, v13 offset:53088
	ds_write_b16_d16_hi v103, v13 offset:53232
	flat_load_dwordx4 v[42:45], v[56:57]
	s_nop 0
	flat_load_dwordx4 v[54:57], v[68:69]
	s_nop 0
	flat_load_dwordx4 v[66:69], v[58:59]
	s_nop 0
	flat_load_dwordx4 v[70:73], v[70:71]
	v_fma_f32 v0, -v104, v105, 1.0
	v_fmac_f32_e32 v105, v0, v105
	v_div_scale_f32 v0, vcc, v101, s39, v101
	v_mul_f32_e32 v10, v0, v105
	v_fma_f32 v11, -v104, v10, v0
	v_fmac_f32_e32 v10, v11, v105
	v_fma_f32 v0, -v104, v10, v0
	v_ashrrev_i32_e32 v11, 2, v39
	v_div_fmas_f32 v0, v0, v105, v10
	v_bfi_b32 v99, -16, v11, v39
	v_div_fixup_f32 v0, v0, s39, v101
	v_and_b32_e32 v12, -16, v11
	v_mul_lo_u32 v11, v99, s38
	v_and_b32_e32 v100, 48, v39
	s_mov_b32 s0, 0xc2fc0000
	v_add3_u32 v11, 0, v11, v100
	v_cmp_gt_f32_e32 vcc, s0, v0
	s_waitcnt lgkmcnt(0)
	s_barrier
	ds_read_b128 v[46:49], v11
	ds_read_b128 v[50:53], v11 offset:64
	ds_read_b128 v[58:61], v11 offset:128
	ds_read_b128 v[62:65], v11 offset:192
	v_cndmask_b32_e32 v11, 0, v216, vcc
	v_add_f32_e32 v0, v0, v11
	v_exp_f32_e32 v0, v0
	s_and_b64 s[0:1], vcc, exec
	s_cselect_b32 s0, 0xffffffc0, 0
	v_cvt_f32_ubyte0_e32 v10, s31
	v_ldexp_f32 v0, v0, s0
	v_mul_f32_e32 v101, v0, v10
	v_mul_i32_i24_e32 v0, -4, v98
	v_add3_u32 v0, v0, v12, v80
	v_subrev_u32_e32 v0, s28, v0
	v_add_u32_e32 v102, 0x8f, v12
	v_lshlrev_b32_e32 v103, 3, v98
	v_mul_u32_u24_e32 v104, 0x90, v80
	v_subrev_u32_e32 v105, 63, v12
	v_add_u32_e32 v107, 0x4d, v0
	v_lshlrev_b32_e32 v80, 1, v38
	v_lshlrev_b32_e32 v82, 1, v40
	v_mov_b32_e32 v34, 0
	v_mov_b32_e32 v35, v108
	v_mov_b32_e32 v36, v108
	v_mov_b32_e32 v37, v108
	v_mov_b32_e32 v38, v108
	v_mov_b32_e32 v39, v108
	v_mov_b32_e32 v40, v108
	v_mov_b32_e32 v41, v108
	v_mov_b32_e32 v30, v108
	v_mov_b32_e32 v31, v108
	v_mov_b32_e32 v32, v108
	v_mov_b32_e32 v33, v108
	v_mov_b32_e32 v26, v108
	v_mov_b32_e32 v27, v108
	v_mov_b32_e32 v28, v108
	v_mov_b32_e32 v29, v108
	v_mov_b32_e32 v22, v108
	v_mov_b32_e32 v23, v108
	v_mov_b32_e32 v24, v108
	v_mov_b32_e32 v25, v108
	v_mov_b32_e32 v18, v108
	v_mov_b32_e32 v19, v108
	v_mov_b32_e32 v20, v108
	v_mov_b32_e32 v21, v108
	v_mov_b32_e32 v14, v108
	v_mov_b32_e32 v15, v108
	v_mov_b32_e32 v16, v108
	v_mov_b32_e32 v17, v108
	v_mov_b32_e32 v10, v108
	v_mov_b32_e32 v11, v108
	v_mov_b32_e32 v12, v108
	v_mov_b32_e32 v13, v108
	s_branch .LBB0_110

; __device__ __forceinline__ int tidx() { int t = threadIdx.x; asm volatile("" : "+v"(t)); return t; }
; __device__ __forceinline__ float shx(float v, int mask, int lane) { return __int_as_float(__builtin_amdgcn_ds_bpermute((lane ^ mask) << 2, __float_as_int(v))); }
; __device__ __forceinline__ size_t pidx(int row, int col) { return (size_t)(col >> 7) * ((size_t)T * 128) + (size_t)row * 128 + (col & 127); }
; __device__ __forceinline__ void stage_rows128_norm(bf16_t* dst, const bf16_t* P, int r0, int rstride, int col, const float* __restrict__ gain, float qs) {
;     const int tid = tidx(), lane = tid & 63;
;     const f32x4 g0 = *(const f32x4*)(gain + (tid & 15) * 8), g1 = *(const f32x4*)(gain + (tid & 15) * 8 + 4);
; #pragma unroll
;     for (int i = 0; i < 4; ++i) {
;         const int idx = tid + 512 * i, r = idx >> 4, ch = idx & 15;
;         const u32x4 raw = *(const u32x4*)(P + pidx(r0 + r * rstride, col + ch * 8));
;         float v[8] = {bflo(raw[0]), bfhi(raw[0]), bflo(raw[1]), bfhi(raw[1]), bflo(raw[2]), bfhi(raw[2]), bflo(raw[3]), bfhi(raw[3])};
;         float ss = 0.f;
; #pragma unroll
;         for (int j = 0; j < 8; ++j) ss += v[j] * v[j];
;         ss += shx(ss, 1, lane); ss += shx(ss, 2, lane); ss += shx(ss, 4, lane); ss += shx(ss, 8, lane);
;         const float inv = rsqrtf(ss * (1.f / 128.f) + EPS) * qs;
; __device__ __forceinline__ void sb_item(const Params& p, int item, int l, unsigned char* lds) {
;     const int tid = tidx(), w = tid >> 6, lane = tid & 63, fr = lane & 15, fq = lane >> 4;
;     const bf16_t* P = (const bf16_t*)(p.ws + W_PROJ);
;     bf16_t* OSB = (bf16_t*)(p.ws + W_OCAT);
;     const int head = item >> 6, I = 63 - (item & 63);
;     bf16_t* Qs = (bf16_t*)(lds + AT_Q); float* flags = (float*)(lds + AT_F);
;     const float* gq = p.in[7] + l * 128; const float* gk = p.in[8] + l * 128;
;     const f32x4 gk0 = *(const f32x4*)(gk + (tid & 15) * 8), gk1 = *(const f32x4*)(gk + (tid & 15) * 8 + 4);
;     const int kcol = C_KSB + head * 128, vcol = C_VSB + head * 128;
;     __syncthreads();
;     TileRegs tr;
;     int J = 2 * I + 1;
;     tile_load(tr, P, 64 * J, 1, kcol, vcol, tid);
;     stage_rows128_norm(Qs, P, 128 * I, 1, C_QSB + head * 128, gq, 0.08838834764831845f);
;     tile_write(tr, lds + AT_BUF, gk0, gk1, tid, lane);
;     tile_load(tr, P, 64 * (J - 1), 1, kcol, vcol, tid);
.LBB0_120:
	s_andn2_b64 vcc, exec, s[0:1]
	s_cbranch_vccnz .LBB0_84
	s_and_b32 s0, s13, 63
	v_mov_b32_e32 v52, v185
	s_lshl_b32 s1, s0, 1
	s_or_b32 s16, s1, 1
	v_lshlrev_b32_e32 v0, 3, v52
	v_and_b32_e32 v96, 0x78, v0
	v_readlane_b32 s4, v245, 55
	s_lshl_b32 s1, s15, 1
	s_lshl_b32 s17, s0, 7
	s_andn2_b32 s0, 63, s15
	v_lshlrev_b32_e32 v0, 2, v96
	v_readlane_b32 s5, v245, 56
	s_and_b32 s74, s1, 0xffffff80
	s_addk_i32 s1, 0x300
	s_nop 2
	global_load_dwordx4 v[2:5], v0, s[4:5] offset:16
	global_load_dwordx4 v[6:9], v0, s[4:5]
	s_lshl_b32 s4, s0, 7
	s_ashr_i32 s0, s1, 7
	s_ashr_i32 s1, s0, 31
	v_ashrrev_i32_e32 v72, 3, v52
	s_waitcnt vmcnt(0)
	v_add_u32_e32 v20, 0x200, v52
	s_add_i32 s5, s74, 0x600
	s_or_b32 s18, s4, 64
	s_lshl_b64 s[44:45], s[0:1], 21
	v_lshlrev_b32_e32 v16, 1, v72
	v_ashrrev_i32_e32 v54, 4, v20
	s_add_u32 s0, s2, s44
	v_and_b32_e32 v44, 0xf0, v16
	v_add_u32_e32 v16, s18, v54
	s_addc_u32 s1, s3, s45
	v_lshlrev_b32_e32 v0, 1, v96
	v_ashrrev_i32_e32 v17, 31, v16
	v_lshl_add_u64 v[38:39], s[0:1], 0, v[0:1]
	v_lshlrev_b64 v[16:17], 8, v[16:17]
	v_ashrrev_i32_e32 v61, 3, v20
	v_and_b32_e32 v87, 63, v52
	v_add_u32_e32 v14, s5, v72
	v_lshl_add_u64 v[18:19], v[38:39], 0, v[16:17]
	v_add_u32_e32 v16, s5, v61
	v_or_b32_e32 v10, s18, v87
	v_ashrrev_i32_e32 v53, 4, v52
	v_ashrrev_i32_e32 v14, 7, v14
	v_ashrrev_i32_e32 v16, 7, v16
	v_lshlrev_b32_e32 v10, 8, v10
	v_mov_b32_e32 v11, v1
	v_add_u32_e32 v12, s18, v53
	v_ashrrev_i32_e32 v15, 31, v14
	v_ashrrev_i32_e32 v17, 31, v16
	v_lshl_add_u64 v[10:11], s[2:3], 0, v[10:11]
	v_ashrrev_i32_e32 v13, 31, v12
	v_lshlrev_b64 v[42:43], 21, v[14:15]
	v_lshlrev_b64 v[46:47], 21, v[16:17]
	v_lshlrev_b32_e32 v16, 1, v61
	v_lshlrev_b64 v[12:13], 8, v[12:13]
	v_lshl_add_u64 v[14:15], v[10:11], 0, v[42:43]
	v_mov_b32_e32 v45, v1
	v_lshl_add_u64 v[10:11], v[10:11], 0, v[46:47]
	v_and_b32_e32 v48, 0xf0, v16
	v_mov_b32_e32 v49, v1
	s_ashr_i32 s0, s15, 6
	v_lshl_add_u64 v[12:13], v[38:39], 0, v[12:13]
	v_lshl_add_u64 v[14:15], v[14:15], 0, v[44:45]
	v_lshl_add_u64 v[10:11], v[10:11], 0, v[48:49]
	v_mov_b32_e32 v60, v185
	s_ashr_i32 s1, s0, 31
	s_waitcnt lgkmcnt(0)
	s_barrier
	flat_load_dwordx4 v[30:33], v[12:13]
	s_nop 0
	flat_load_dwordx4 v[14:17], v[14:15]
	s_nop 0
	flat_load_dwordx4 v[26:29], v[18:19]
	s_nop 0
	flat_load_dwordx4 v[10:13], v[10:11]
	s_lshl_b64 s[0:1], s[0:1], 21
	v_lshlrev_b32_e32 v18, 3, v60
	v_ashrrev_i32_e32 v70, 4, v60
	v_and_b32_e32 v20, 0x78, v18
	s_add_u32 s0, s2, s0
	v_add_u32_e32 v18, s4, v70
	s_addc_u32 s1, s3, s1
	v_lshlrev_b32_e32 v40, 1, v20
	v_mov_b32_e32 v41, v1
	v_ashrrev_i32_e32 v19, 31, v18
	v_lshl_add_u64 v[50:51], s[0:1], 0, v[40:41]
	v_lshlrev_b64 v[18:19], 8, v[18:19]
	v_lshl_add_u64 v[18:19], v[50:51], 0, v[18:19]
	flat_load_dwordx4 v[34:37], v[18:19]
	s_mov_b64 s[0:1], 0x2000
	v_lshl_add_u64 v[152:153], v[18:19], 0, s[0:1]
	flat_load_dwordx4 v[156:159], v[152:153]
	v_lshl_add_u64 v[152:153], v[152:153], 0, s[0:1]
	flat_load_dwordx4 v[160:163], v[152:153]
	v_lshl_add_u64 v[152:153], v[152:153], 0, s[0:1]
	flat_load_dwordx4 v[164:167], v[152:153]
	v_readlane_b32 s0, v245, 53
	v_lshlrev_b32_e32 v18, 2, v20
	v_readlane_b32 s1, v245, 54
	s_nop 4
	global_load_dwordx4 v[22:25], v18, s[0:1]
	s_nop 0
	global_load_dwordx4 v[18:21], v18, s[0:1] offset:16
	v_lshlrev_b32_e32 v55, 2, v60
	v_bitop3_b32 v41, v55, 4, v211 bitop3:0x6c
	v_add_u32_e32 v40, 0, v40
	s_movk_i32 s5, 0x110
	v_add_u32_e32 v92, 0, v0
	v_lshlrev_b32_e32 v90, 2, v87
	v_xor_b32_e32 v98, 4, v90
	v_xor_b32_e32 v99, 8, v90
	v_xor_b32_e32 v100, 16, v90
	v_xor_b32_e32 v101, 32, v90
	v_or_b32_e32 v91, s4, v87
	s_brev_b32 s76, 60
	s_movk_i32 s18, 0x48
	v_lshl_add_u32 v86, v87, 1, 0
	v_and_b32_e32 v105, 48, v52
	v_xor_b32_e32 v108, 64, v90
	v_xor_b32_e32 v109, 0x80, v90
	v_xor_b32_e32 v110, 0xc0, v90
	s_movk_i32 s78, 0xc000
	v_cmp_eq_u32_e64 s[36:37], 0, v87
	v_cmp_lt_u32_e64 s[38:39], 15, v87
	v_mov_b32_e32 v114, 1.0
	s_mov_b32 s25, 0xc2a00000
	s_mov_b32 s79, -1
	s_waitcnt vmcnt(0) lgkmcnt(0)
	v_and_b32_e32 v79, 0xffff0000, v28
	v_lshlrev_b32_e32 v68, 16, v34
	v_and_b32_e32 v69, 0xffff0000, v34
	v_lshlrev_b32_e32 v58, 16, v37
	v_and_b32_e32 v59, 0xffff0000, v37
	v_lshlrev_b32_e32 v62, 16, v36
	v_and_b32_e32 v63, 0xffff0000, v36
	v_lshlrev_b32_e32 v36, 16, v35
	v_and_b32_e32 v37, 0xffff0000, v35
	v_pk_mul_f32 v[34:35], v[68:69], v[68:69]
	v_pk_mul_f32 v[66:67], v[36:37], v[36:37]
	v_add_f32_e32 v34, v34, v35
	v_add_f32_e32 v34, v66, v34
	v_pk_mul_f32 v[64:65], v[62:63], v[62:63]
	v_add_f32_e32 v34, v67, v34
	v_add_f32_e32 v34, v64, v34
	v_pk_mul_f32 v[56:57], v[58:59], v[58:59]
	v_add_f32_e32 v34, v65, v34
	v_add_f32_e32 v34, v56, v34
	v_add_f32_e32 v34, v57, v34
	ds_bpermute_b32 v35, v41, v34
	v_bitop3_b32 v57, v55, 8, v211 bitop3:0x6c
	v_bitop3_b32 v56, v55, 16, v211 bitop3:0x6c
	v_bitop3_b32 v55, v55, 32, v211 bitop3:0x6c
	s_waitcnt lgkmcnt(0)
	v_add_f32_e32 v34, v34, v35
	ds_bpermute_b32 v35, v57, v34
	s_waitcnt lgkmcnt(0)
	v_add_f32_e32 v34, v34, v35
	ds_bpermute_b32 v35, v56, v34
	s_waitcnt lgkmcnt(0)
	v_add_f32_e32 v34, v34, v35
	ds_bpermute_b32 v35, v55, v34
	s_waitcnt lgkmcnt(0)
; __device__ __forceinline__ unsigned pk2(float lo, float hi) { const f32v2_t v = {lo, hi}; return __builtin_bit_cast(unsigned, __builtin_convertvector(v, bf16v2_t)); }
; __device__ __forceinline__ int tidx() { int t = threadIdx.x; asm volatile("" : "+v"(t)); return t; }
; __device__ __forceinline__ float shx(float v, int mask, int lane) { return __int_as_float(__builtin_amdgcn_ds_bpermute((lane ^ mask) << 2, __float_as_int(v))); }
; __device__ __forceinline__ size_t pidx(int row, int col) { return (size_t)(col >> 7) * ((size_t)T * 128) + (size_t)row * 128 + (col & 127); }
; __device__ __forceinline__ float bflo(unsigned u) { return __uint_as_float(u << 16); }
; __device__ __forceinline__ float bfhi(unsigned u) { return __uint_as_float(u & 0xffff0000u); }
; __device__ __forceinline__ void stage_rows128_norm(bf16_t* dst, const bf16_t* P, int r0, int rstride, int col, const float* __restrict__ gain, float qs) {
;     const int tid = tidx(), lane = tid & 63;
;     const f32x4 g0 = *(const f32x4*)(gain + (tid & 15) * 8), g1 = *(const f32x4*)(gain + (tid & 15) * 8 + 4);
; #pragma unroll
;     for (int i = 0; i < 4; ++i) {
;         const int idx = tid + 512 * i, r = idx >> 4, ch = idx & 15;
;         const u32x4 raw = *(const u32x4*)(P + pidx(r0 + r * rstride, col + ch * 8));
;         float v[8] = {bflo(raw[0]), bfhi(raw[0]), bflo(raw[1]), bfhi(raw[1]), bflo(raw[2]), bfhi(raw[2]), bflo(raw[3]), bfhi(raw[3])};
;         float ss = 0.f;
; #pragma unroll
;         for (int j = 0; j < 8; ++j) ss += v[j] * v[j];
;         ss += shx(ss, 1, lane); ss += shx(ss, 2, lane); ss += shx(ss, 4, lane); ss += shx(ss, 8, lane);
;         const float inv = rsqrtf(ss * (1.f / 128.f) + EPS) * qs;
;         u32x4 o = {pk2(v[0] * inv * g0[0], v[1] * inv * g0[1]), pk2(v[2] * inv * g0[2], v[3] * inv * g0[3]),
;                    pk2(v[4] * inv * g1[0], v[5] * inv * g1[1]), pk2(v[6] * inv * g1[2], v[7] * inv * g1[3])};
;         *(u32x4*)(dst + r * 136 + ch * 8) = o;
;     }
; }
	v_add_f32_e32 v34, v34, v35
	v_fmamk_f32 v34, v34, 0x3c000000, v184
	v_mul_f32_e32 v35, 0x4b800000, v34
	v_cmp_gt_f32_e32 vcc, s90, v34
	s_nop 1
	v_cndmask_b32_e32 v34, v34, v35, vcc
	v_rsq_f32_e32 v34, v34
	s_nop 0
	v_mul_f32_e32 v35, 0x45800000, v34
	v_cndmask_b32_e32 v34, v34, v35, vcc
	v_mul_f32_e32 v34, 0x3db504f3, v34
	v_pk_mul_f32 v[64:65], v[34:35], v[68:69] op_sel_hi:[0,1]
	v_pk_mul_f32 v[36:37], v[34:35], v[36:37] op_sel_hi:[0,1]
	v_pk_mul_f32 v[62:63], v[34:35], v[62:63] op_sel_hi:[0,1]
	v_pk_mul_f32 v[34:35], v[34:35], v[58:59] op_sel_hi:[0,1]
	v_pk_mul_f32 v[58:59], v[22:23], v[64:65]
	v_pk_mul_f32 v[36:37], v[24:25], v[36:37]
	v_pk_mul_f32 v[62:63], v[18:19], v[62:63]
	v_pk_mul_f32 v[64:65], v[20:21], v[34:35]
	v_cvt_pk_bf16_f32 v34, v58, v59
	v_cvt_pk_bf16_f32 v35, v36, v37
	v_cvt_pk_bf16_f32 v36, v62, v63
	v_cvt_pk_bf16_f32 v37, v64, v65
	v_mad_u64_u32 v[58:59], s[0:1], v70, s5, v[40:41]
	ds_write_b128 v58, v[34:37]
	v_add_u32_e32 v34, 0x200, v60
	v_ashrrev_i32_e32 v73, 4, v34
	v_add_u32_e32 v34, s4, v73
	v_ashrrev_i32_e32 v35, 31, v34
	v_lshlrev_b64 v[34:35], 8, v[34:35]
	v_lshl_add_u64 v[34:35], v[50:51], 0, v[34:35]
	v_mov_b64_e32 v[34:35], v[156:157]
	v_mov_b64_e32 v[36:37], v[158:159]
	s_waitcnt lgkmcnt(0)
	v_lshlrev_b32_e32 v64, 16, v34
	v_and_b32_e32 v65, 0xffff0000, v34
	v_lshlrev_b32_e32 v58, 16, v37
	v_and_b32_e32 v59, 0xffff0000, v37
	v_lshlrev_b32_e32 v62, 16, v36
	v_and_b32_e32 v63, 0xffff0000, v36
	v_lshlrev_b32_e32 v36, 16, v35
	v_and_b32_e32 v37, 0xffff0000, v35
	v_pk_mul_f32 v[70:71], v[64:65], v[64:65]
	v_pk_mul_f32 v[68:69], v[36:37], v[36:37]
	v_add_f32_e32 v70, v70, v71
	v_add_f32_e32 v68, v68, v70
	v_pk_mul_f32 v[66:67], v[62:63], v[62:63]
	v_add_f32_e32 v68, v69, v68
	v_add_f32_e32 v66, v66, v68
	v_pk_mul_f32 v[34:35], v[58:59], v[58:59]
	v_add_f32_e32 v66, v67, v66
	v_add_f32_e32 v34, v34, v66
	v_add_f32_e32 v34, v35, v34
	ds_bpermute_b32 v35, v41, v34
	s_waitcnt lgkmcnt(0)
	v_add_f32_e32 v34, v34, v35
	ds_bpermute_b32 v35, v57, v34
	s_waitcnt lgkmcnt(0)
	v_add_f32_e32 v34, v34, v35
	ds_bpermute_b32 v35, v56, v34
	s_waitcnt lgkmcnt(0)
	v_add_f32_e32 v66, v34, v35
	ds_bpermute_b32 v67, v55, v66
	v_add_u32_e32 v34, 0x400, v60
	v_ashrrev_i32_e32 v78, 4, v34
	v_add_u32_e32 v34, s4, v78
	v_ashrrev_i32_e32 v35, 31, v34
	s_waitcnt lgkmcnt(0)
	v_add_f32_e32 v66, v66, v67
	v_fmamk_f32 v66, v66, 0x3c000000, v184
	v_mul_f32_e32 v67, 0x4b800000, v66
	v_cmp_gt_f32_e32 vcc, s90, v66
	v_lshlrev_b64 v[34:35], 8, v[34:35]
	v_lshl_add_u64 v[68:69], v[50:51], 0, v[34:35]
	v_cndmask_b32_e32 v66, v66, v67, vcc
	v_rsq_f32_e32 v70, v66
	v_mad_u64_u32 v[66:67], s[0:1], v73, s5, v[40:41]
	s_movk_i32 s0, 0x88
	v_mul_f32_e32 v34, 0x45800000, v70
	v_cndmask_b32_e32 v34, v70, v34, vcc
	v_mul_f32_e32 v34, 0x3db504f3, v34
	v_pk_mul_f32 v[64:65], v[34:35], v[64:65] op_sel_hi:[0,1]
	v_pk_mul_f32 v[36:37], v[34:35], v[36:37] op_sel_hi:[0,1]
	v_pk_mul_f32 v[62:63], v[34:35], v[62:63] op_sel_hi:[0,1]
	v_pk_mul_f32 v[34:35], v[34:35], v[58:59] op_sel_hi:[0,1]
	v_pk_mul_f32 v[58:59], v[22:23], v[64:65]
	v_pk_mul_f32 v[36:37], v[24:25], v[36:37]
	v_pk_mul_f32 v[62:63], v[18:19], v[62:63]
	v_pk_mul_f32 v[64:65], v[20:21], v[34:35]
	v_cvt_pk_bf16_f32 v34, v58, v59
	v_cvt_pk_bf16_f32 v35, v36, v37
	v_cvt_pk_bf16_f32 v36, v62, v63
	v_cvt_pk_bf16_f32 v37, v64, v65
	ds_write_b128 v66, v[34:37]
	v_mov_b64_e32 v[34:35], v[160:161]
	v_mov_b64_e32 v[36:37], v[162:163]
	v_and_b32_e32 v63, 0x1ffffff8, v72
	v_and_b32_e32 v65, 0x1ffffff8, v61
	v_mul_lo_u32 v97, v53, s0
	v_mul_lo_u32 v103, v54, s0
	v_add_u32_e32 v62, s4, v53
	v_add_u32_e32 v64, s4, v54
	v_mul_lo_u32 v102, v63, s18
	v_ashrrev_i32_e32 v63, 31, v62
	v_mul_lo_u32 v104, v65, s18
	v_ashrrev_i32_e32 v65, 31, v64
	v_lshlrev_b64 v[62:63], 8, v[62:63]
	v_lshlrev_b64 v[64:65], 8, v[64:65]
	v_lshl_add_u64 v[62:63], v[38:39], 0, v[62:63]
	v_lshl_add_u64 v[38:39], v[38:39], 0, v[64:65]
	v_lshl_add_u32 v94, v102, 1, v86
	v_lshl_add_u32 v95, v97, 1, v92
	v_lshl_add_u32 v92, v103, 1, v92
	v_lshl_add_u32 v86, v104, 1, v86
	v_ashrrev_i32_e32 v59, 6, v52
	v_and_b32_e32 v58, 15, v52
	v_mul_u32_u24_e32 v112, 0x90, v58
	v_mul_u32_u24_e32 v113, 0x110, v58
	s_waitcnt lgkmcnt(0)
	v_lshlrev_b32_e32 v70, 16, v34
	v_and_b32_e32 v71, 0xffff0000, v34
	v_lshlrev_b32_e32 v66, 16, v37
	v_and_b32_e32 v67, 0xffff0000, v37
	v_lshlrev_b32_e32 v68, 16, v36
	v_and_b32_e32 v69, 0xffff0000, v36
	v_lshlrev_b32_e32 v36, 16, v35
	v_and_b32_e32 v37, 0xffff0000, v35
	v_pk_mul_f32 v[76:77], v[70:71], v[70:71]
	v_pk_mul_f32 v[74:75], v[36:37], v[36:37]
	v_add_f32_e32 v0, v76, v77
	v_add_f32_e32 v0, v74, v0
	v_pk_mul_f32 v[72:73], v[68:69], v[68:69]
	v_add_f32_e32 v0, v75, v0
	v_add_f32_e32 v0, v72, v0
	v_pk_mul_f32 v[34:35], v[66:67], v[66:67]
	v_add_f32_e32 v0, v73, v0
	v_add_f32_e32 v0, v34, v0
	v_add_f32_e32 v0, v35, v0
	ds_bpermute_b32 v61, v41, v0
	v_add_u32_e32 v34, 0x600, v60
	v_lshlrev_b32_e32 v74, 16, v30
	v_and_b32_e32 v75, 0xffff0000, v30
	v_ashrrev_i32_e32 v93, 4, v34
	s_waitcnt lgkmcnt(0)
	v_add_f32_e32 v0, v0, v61
	ds_bpermute_b32 v72, v57, v0
	v_mad_u64_u32 v[60:61], s[0:1], v78, s5, v[40:41]
	v_add_u32_e32 v34, s4, v93
	v_lshlrev_b32_e32 v78, 16, v28
	s_waitcnt lgkmcnt(0)
	v_add_f32_e32 v0, v0, v72
	ds_bpermute_b32 v61, v56, v0
	v_ashrrev_i32_e32 v35, 31, v34
	v_lshlrev_b64 v[34:35], 8, v[34:35]
	v_lshl_add_u64 v[34:35], v[50:51], 0, v[34:35]
	v_lshlrev_b32_e32 v50, 16, v33
	s_waitcnt lgkmcnt(0)
	v_add_f32_e32 v0, v0, v61
	ds_bpermute_b32 v61, v55, v0
	v_and_b32_e32 v51, 0xffff0000, v33
	v_lshlrev_b32_e32 v72, 16, v32
	v_and_b32_e32 v73, 0xffff0000, v32
	v_lshlrev_b32_e32 v32, 16, v31
	s_waitcnt lgkmcnt(0)
; __device__ __forceinline__ unsigned pk2(float lo, float hi) { const f32v2_t v = {lo, hi}; return __builtin_bit_cast(unsigned, __builtin_convertvector(v, bf16v2_t)); }
; __device__ __forceinline__ float shx(float v, int mask, int lane) { return __int_as_float(__builtin_amdgcn_ds_bpermute((lane ^ mask) << 2, __float_as_int(v))); }
; __device__ __forceinline__ void stage_rows128_norm(bf16_t* dst, const bf16_t* P, int r0, int rstride, int col, const float* __restrict__ gain, float qs) {
;     ...
;         const int idx = tid + 512 * i, r = idx >> 4, ch = idx & 15;
;         const u32x4 raw = *(const u32x4*)(P + pidx(r0 + r * rstride, col + ch * 8));
;         float v[8] = {bflo(raw[0]), bfhi(raw[0]), bflo(raw[1]), bfhi(raw[1]), bflo(raw[2]), bfhi(raw[2]), bflo(raw[3]), bfhi(raw[3])};
;         float ss = 0.f;
; #pragma unroll
;         for (int j = 0; j < 8; ++j) ss += v[j] * v[j];
;         ss += shx(ss, 1, lane); ss += shx(ss, 2, lane); ss += shx(ss, 4, lane); ss += shx(ss, 8, lane);
;         const float inv = rsqrtf(ss * (1.f / 128.f) + EPS) * qs;
;         u32x4 o = {pk2(v[0] * inv * g0[0], v[1] * inv * g0[1]), pk2(v[2] * inv * g0[2], v[3] * inv * g0[3]),
;                    pk2(v[4] * inv * g1[0], v[5] * inv * g1[1]), pk2(v[6] * inv * g1[2], v[7] * inv * g1[3])};
;         *(u32x4*)(dst + r * 136 + ch * 8) = o;
;     }
; }
; __device__ __forceinline__ void tile_write(const TileRegs& t, unsigned char* buf, const f32x4& g0, const f32x4& g1, int tid, int lane) {
;     bf16_t* Ks = (bf16_t*)buf; bf16_t* VT = (bf16_t*)(buf + AT_VOFF);
; #pragma unroll
;     for (int i = 0; i < 2; ++i) {
;         const int idx = tid + 512 * i, r = idx >> 4, ch = idx & 15;
;         const u32x4 raw = t.k[i];
;         float v[8] = {bflo(raw[0]), bfhi(raw[0]), bflo(raw[1]), bfhi(raw[1]), bflo(raw[2]), bfhi(raw[2]), bflo(raw[3]), bfhi(raw[3])};
;         float ss = 0.f;
; #pragma unroll
;         for (int j = 0; j < 8; ++j) ss += v[j] * v[j];
;         ss += shx(ss, 1, lane); ss += shx(ss, 2, lane); ss += shx(ss, 4, lane); ss += shx(ss, 8, lane);
;         const float inv = rsqrtf(ss * (1.f / 128.f) + EPS);
;         u32x4 o = {pk2(v[0] * inv * g0[0], v[1] * inv * g0[1]), pk2(v[2] * inv * g0[2], v[3] * inv * g0[3]),
;                    pk2(v[4] * inv * g1[0], v[5] * inv * g1[1]), pk2(v[6] * inv * g1[2], v[7] * inv * g1[3])};
;         *(u32x4*)(Ks + r * 136 + ch * 8) = o;
	v_add_f32_e32 v0, v0, v61
	v_fmamk_f32 v0, v0, 0x3c000000, v184
	v_mul_f32_e32 v30, 0x4b800000, v0
	v_cmp_gt_f32_e32 vcc, s90, v0
	v_and_b32_e32 v33, 0xffff0000, v31
	v_lshlrev_b32_e32 v76, 16, v29
	v_cndmask_b32_e32 v0, v0, v30, vcc
	v_rsq_f32_e32 v0, v0
	v_and_b32_e32 v77, 0xffff0000, v29
	v_mov_b32_e32 v85, v75
	v_mov_b32_e32 v83, v74
	v_mul_f32_e32 v28, 0x45800000, v0
	v_cndmask_b32_e32 v0, v0, v28, vcc
	v_mul_f32_e32 v0, 0x3db504f3, v0
	v_pk_mul_f32 v[28:29], v[0:1], v[70:71] op_sel_hi:[0,1]
	v_pk_mul_f32 v[30:31], v[0:1], v[36:37] op_sel_hi:[0,1]
	v_pk_mul_f32 v[36:37], v[0:1], v[68:69] op_sel_hi:[0,1]
	v_pk_mul_f32 v[66:67], v[0:1], v[66:67] op_sel_hi:[0,1]
	v_pk_mul_f32 v[28:29], v[22:23], v[28:29]
	v_pk_mul_f32 v[30:31], v[24:25], v[30:31]
	v_pk_mul_f32 v[36:37], v[18:19], v[36:37]
	v_pk_mul_f32 v[66:67], v[20:21], v[66:67]
	v_cvt_pk_bf16_f32 v28, v28, v29
	v_cvt_pk_bf16_f32 v29, v30, v31
	v_cvt_pk_bf16_f32 v30, v36, v37
	v_cvt_pk_bf16_f32 v31, v66, v67
	ds_write_b128 v60, v[28:31]
	v_mov_b64_e32 v[28:29], v[164:165]
	v_mov_b64_e32 v[30:31], v[166:167]
	v_and_b32_e32 v37, 0xffff0000, v26
	v_lshlrev_b32_e32 v34, 16, v27
	v_and_b32_e32 v35, 0xffff0000, v27
	v_lshlrev_b32_e32 v36, 16, v26
	v_mov_b32_e32 v84, v37
	v_pk_mul_f32 v[26:27], v[50:51], v[50:51]
	v_pk_mul_f32 v[60:61], v[72:73], v[72:73]
	v_pk_mul_f32 v[66:67], v[32:33], v[32:33]
	v_pk_mul_f32 v[68:69], v[76:77], v[76:77]
	v_pk_mul_f32 v[70:71], v[78:79], v[78:79]
	v_pk_mul_f32 v[80:81], v[34:35], v[34:35]
	v_mov_b32_e32 v82, v36
	v_pk_mul_f32 v[84:85], v[84:85], v[84:85]
	v_mov_b32_e32 v88, v80
	v_mov_b32_e32 v89, v66
	v_mov_b32_e32 v66, v81
	v_mov_b32_e32 v80, v70
	v_mov_b32_e32 v81, v60
	v_mov_b32_e32 v60, v71
	v_mov_b32_e32 v70, v68
	v_mov_b32_e32 v71, v26
	v_mov_b32_e32 v26, v69
	v_pk_fma_f32 v[68:69], v[82:83], v[82:83], v[84:85]
	v_lshlrev_b32_e32 v0, 8, v91
	v_pk_add_f32 v[68:69], v[88:89], v[68:69]
	s_waitcnt lgkmcnt(0)
	v_lshlrev_b32_e32 v82, 16, v28
	v_pk_add_f32 v[66:67], v[66:67], v[68:69]
	v_and_b32_e32 v83, 0xffff0000, v28
	v_pk_add_f32 v[66:67], v[80:81], v[66:67]
	v_lshlrev_b32_e32 v80, 16, v29
	v_pk_add_f32 v[60:61], v[60:61], v[66:67]
	v_lshl_add_u64 v[66:67], s[2:3], 0, v[0:1]
	v_pk_add_f32 v[60:61], v[70:71], v[60:61]
	v_lshl_add_u64 v[64:65], v[66:67], 0, v[42:43]
	v_pk_add_f32 v[26:27], v[26:27], v[60:61]
	ds_bpermute_b32 v61, v98, v27
	ds_bpermute_b32 v60, v98, v26
	v_and_b32_e32 v81, 0xffff0000, v29
	v_pk_mul_f32 v[88:89], v[82:83], v[82:83]
	v_lshl_add_u64 v[64:65], v[64:65], 0, v[44:45]
	v_pk_mul_f32 v[84:85], v[80:81], v[80:81]
	s_waitcnt lgkmcnt(0)
	v_pk_add_f32 v[26:27], v[26:27], v[60:61]
	ds_bpermute_b32 v61, v99, v27
	ds_bpermute_b32 v60, v99, v26
	v_lshl_add_u64 v[66:67], v[66:67], 0, v[46:47]
	v_lshl_add_u64 v[66:67], v[66:67], 0, v[48:49]
	s_waitcnt lgkmcnt(0)
	v_pk_add_f32 v[26:27], v[26:27], v[60:61]
	ds_bpermute_b32 v61, v100, v27
	ds_bpermute_b32 v60, v100, v26
	s_waitcnt lgkmcnt(0)
	v_pk_add_f32 v[26:27], v[26:27], v[60:61]
	ds_bpermute_b32 v61, v101, v27
	ds_bpermute_b32 v60, v101, v26
	s_waitcnt lgkmcnt(0)
	v_pk_add_f32 v[26:27], v[26:27], v[60:61]
	s_nop 0
	v_pk_fma_f32 v[26:27], v[26:27], s[76:77], v[184:185] op_sel_hi:[1,0,0]
	v_mad_u64_u32 v[60:61], s[18:19], v93, s5, v[40:41]
	v_mul_f32_e32 v0, 0x4b800000, v27
	v_cmp_gt_f32_e32 vcc, s90, v27
	v_mul_f32_e32 v45, 0x4b800000, v26
	v_cmp_gt_f32_e64 s[0:1], s90, v26
	v_cndmask_b32_e32 v0, v27, v0, vcc
	v_rsq_f32_e32 v0, v0
	v_cndmask_b32_e64 v26, v26, v45, s[0:1]
	v_rsq_f32_e32 v26, v26
	s_mov_b32 s18, 0
	v_mul_f32_e32 v27, 0x45800000, v0
	v_cndmask_b32_e32 v0, v0, v27, vcc
	v_pk_mul_f32 v[68:69], v[0:1], v[74:75] op_sel_hi:[0,1]
	v_pk_mul_f32 v[32:33], v[0:1], v[32:33] op_sel_hi:[0,1]
	v_pk_mul_f32 v[70:71], v[0:1], v[72:73] op_sel_hi:[0,1]
	v_pk_mul_f32 v[50:51], v[0:1], v[50:51] op_sel_hi:[0,1]
	v_add_f32_e32 v0, v88, v89
	v_lshlrev_b32_e32 v74, 16, v30
	v_and_b32_e32 v75, 0xffff0000, v30
	v_add_f32_e32 v0, v84, v0
	v_lshlrev_b32_e32 v72, 16, v31
	v_and_b32_e32 v73, 0xffff0000, v31
	v_pk_mul_f32 v[30:31], v[74:75], v[74:75]
	v_add_f32_e32 v0, v85, v0
	v_add_f32_e32 v0, v30, v0
	v_pk_mul_f32 v[28:29], v[72:73], v[72:73]
	v_add_f32_e32 v0, v31, v0
	v_add_f32_e32 v0, v28, v0
	v_mul_f32_e32 v40, 0x45800000, v26
	v_add_f32_e32 v0, v29, v0
	v_cndmask_b32_e64 v26, v26, v40, s[0:1]
	ds_bpermute_b32 v40, v41, v0
	v_pk_mul_f32 v[30:31], v[26:27], v[78:79] op_sel_hi:[0,1]
	v_pk_mul_f32 v[28:29], v[26:27], v[34:35] op_sel_hi:[0,1]
	v_pk_mul_f32 v[34:35], v[6:7], v[68:69]
	v_pk_mul_f32 v[68:69], v[2:3], v[30:31]
	s_waitcnt lgkmcnt(0)
; __device__ __forceinline__ unsigned pk2(float lo, float hi) { const f32v2_t v = {lo, hi}; return __builtin_bit_cast(unsigned, __builtin_convertvector(v, bf16v2_t)); }
; __device__ __forceinline__ float shx(float v, int mask, int lane) { return __int_as_float(__builtin_amdgcn_ds_bpermute((lane ^ mask) << 2, __float_as_int(v))); }
; __device__ __forceinline__ void tile_write(const TileRegs& t, unsigned char* buf, const f32x4& g0, const f32x4& g1, int tid, int lane) {
;     bf16_t* Ks = (bf16_t*)buf; bf16_t* VT = (bf16_t*)(buf + AT_VOFF);
; #pragma unroll
;     for (int i = 0; i < 2; ++i) {
;         const int idx = tid + 512 * i, r = idx >> 4, ch = idx & 15;
;         const u32x4 raw = t.k[i];
;         float v[8] = {bflo(raw[0]), bfhi(raw[0]), bflo(raw[1]), bfhi(raw[1]), bflo(raw[2]), bfhi(raw[2]), bflo(raw[3]), bfhi(raw[3])};
;         float ss = 0.f;
; #pragma unroll
;         for (int j = 0; j < 8; ++j) ss += v[j] * v[j];
;         ss += shx(ss, 1, lane); ss += shx(ss, 2, lane); ss += shx(ss, 4, lane); ss += shx(ss, 8, lane);
;         const float inv = rsqrtf(ss * (1.f / 128.f) + EPS);
;         u32x4 o = {pk2(v[0] * inv * g0[0], v[1] * inv * g0[1]), pk2(v[2] * inv * g0[2], v[3] * inv * g0[3]),
;                    pk2(v[4] * inv * g1[0], v[5] * inv * g1[1]), pk2(v[6] * inv * g1[2], v[7] * inv * g1[3])};
;         *(u32x4*)(Ks + r * 136 + ch * 8) = o;
;         const u32x4 rv = t.v[i];
;         bf16_t* d = VT + ((idx >> 6) * 8) * 72 + (idx & 63);
;         d[0] = (bf16_t)(rv[0] & 0xffff); d[72] = (bf16_t)(rv[0] >> 16); d[144] = (bf16_t)(rv[1] & 0xffff); d[216] = (bf16_t)(rv[1] >> 16);
;         d[288] = (bf16_t)(rv[2] & 0xffff); d[360] = (bf16_t)(rv[2] >> 16); d[432] = (bf16_t)(rv[3] & 0xffff); d[504] = (bf16_t)(rv[3] >> 16);
;     }
; }
; __device__ __forceinline__ void sb_item(const Params& p, int item, int l, unsigned char* lds) {
;     ...
;     tile_write(tr, lds + AT_BUF, gk0, gk1, tid, lane);
;     tile_load(tr, P, 64 * (J - 1), 1, kcol, vcol, tid);
;     __syncthreads();
;     bf16x8 qf[4];
; #pragma unroll
;     for (int ks = 0; ks < 4; ++ks) qf[ks] = *(const bf16x8*)(Qs + (16 * w + fr) * 136 + 32 * ks + 8 * fq);
;     f32x4 oacc[8];
; #pragma unroll
;     for (int db = 0; db < 8; ++db) oacc[db] = (f32x4){0.f, 0.f, 0.f, 0.f};
;     float R = 1.f;
;     const int tq = 128 * I + 16 * w + fr;
;     constexpr float SB_EXIT = 1e-9f;
;     int cur = 0;
	v_add_f32_e32 v0, v0, v40
	ds_bpermute_b32 v45, v57, v0
	v_pk_mul_f32 v[36:37], v[26:27], v[36:37] op_sel_hi:[0,1]
	v_pk_mul_f32 v[26:27], v[26:27], v[76:77] op_sel_hi:[0,1]
	v_pk_mul_f32 v[40:41], v[2:3], v[70:71]
	v_pk_mul_f32 v[70:71], v[4:5], v[26:27]
	s_waitcnt lgkmcnt(0)
	v_add_f32_e32 v0, v0, v45
	ds_bpermute_b32 v45, v56, v0
	v_cvt_pk_bf16_f32 v26, v34, v35
	v_pk_mul_f32 v[50:51], v[4:5], v[50:51]
	v_pk_mul_f32 v[36:37], v[6:7], v[36:37]
	v_pk_mul_f32 v[56:57], v[8:9], v[28:29]
	s_waitcnt lgkmcnt(0)
	v_add_f32_e32 v0, v0, v45
	ds_bpermute_b32 v31, v55, v0
	v_cvt_pk_bf16_f32 v28, v40, v41
	v_cvt_pk_bf16_f32 v29, v50, v51
	v_cvt_pk_bf16_f32 v30, v36, v37
	v_pk_mul_f32 v[32:33], v[8:9], v[32:33]
	s_waitcnt lgkmcnt(0)
	v_add_f32_e32 v0, v0, v31
	v_fmamk_f32 v0, v0, 0x3c000000, v184
	v_mul_f32_e32 v31, 0x4b800000, v0
	v_cmp_gt_f32_e32 vcc, s90, v0
	v_cvt_pk_bf16_f32 v27, v32, v33
	v_cvt_pk_bf16_f32 v32, v68, v69
	v_cndmask_b32_e32 v0, v0, v31, vcc
	v_rsq_f32_e32 v0, v0
	v_cvt_pk_bf16_f32 v31, v56, v57
	v_cvt_pk_bf16_f32 v33, v70, v71
	v_readlane_b32 s0, v246, 59
	v_mul_f32_e32 v34, 0x45800000, v0
	v_cndmask_b32_e32 v0, v0, v34, vcc
	v_mul_f32_e32 v0, 0x3db504f3, v0
	v_pk_mul_f32 v[34:35], v[0:1], v[82:83] op_sel_hi:[0,1]
	v_pk_mul_f32 v[36:37], v[0:1], v[80:81] op_sel_hi:[0,1]
	v_pk_mul_f32 v[40:41], v[0:1], v[74:75] op_sel_hi:[0,1]
	v_pk_mul_f32 v[50:51], v[0:1], v[72:73] op_sel_hi:[0,1]
	v_pk_mul_f32 v[22:23], v[22:23], v[34:35]
	v_pk_mul_f32 v[24:25], v[24:25], v[36:37]
	v_pk_mul_f32 v[34:35], v[18:19], v[40:41]
	v_pk_mul_f32 v[36:37], v[20:21], v[50:51]
	v_cvt_pk_bf16_f32 v18, v22, v23
	v_cvt_pk_bf16_f32 v19, v24, v25
	v_cvt_pk_bf16_f32 v20, v34, v35
	v_cvt_pk_bf16_f32 v21, v36, v37
	ds_write_b128 v60, v[18:21]
	ds_write_b128 v95, v[26:29] offset:34816
	ds_write_b16 v94, v14 offset:52224
	ds_write_b16_d16_hi v94, v14 offset:52368
	ds_write_b16 v94, v15 offset:52512
	ds_write_b16_d16_hi v94, v15 offset:52656
	ds_write_b16 v94, v16 offset:52800
	ds_write_b16_d16_hi v94, v16 offset:52944
	ds_write_b16 v94, v17 offset:53088
	ds_write_b16_d16_hi v94, v17 offset:53232
	ds_write_b128 v92, v[30:33] offset:34816
	ds_write_b16 v86, v10 offset:52224
	ds_write_b16_d16_hi v86, v10 offset:52368
	ds_write_b16 v86, v11 offset:52512
	ds_write_b16_d16_hi v86, v11 offset:52656
	ds_write_b16 v86, v12 offset:52800
	ds_write_b16_d16_hi v86, v12 offset:52944
	ds_write_b16 v86, v13 offset:53088
	ds_write_b16_d16_hi v86, v13 offset:53232
	flat_load_dwordx4 v[10:13], v[62:63]
	flat_load_dwordx4 v[14:17], v[64:65]
	flat_load_dwordx4 v[18:21], v[38:39]
	flat_load_dwordx4 v[30:33], v[66:67]
	v_add_u32_e32 v50, s17, v54
	v_lshlrev_b32_e32 v0, 4, v59
	v_lshl_add_u32 v107, v59, 2, s0
	s_add_u32 s0, s44, 0x17214000
	v_ashrrev_i32_e32 v51, 31, v50
	v_or_b32_e32 v22, v0, v58
	s_addc_u32 s1, s45, 0
	v_lshlrev_b64 v[50:51], 8, v[50:51]
	v_mul_lo_u32 v22, v22, s5
	v_lshl_add_u64 v[88:89], s[0:1], 0, v[50:51]
	v_add_u32_e32 v50, s17, v53
	v_add3_u32 v38, 0, v22, v105
	v_ashrrev_i32_e32 v51, 31, v50
	s_waitcnt lgkmcnt(0)
	s_barrier
	ds_read_b128 v[22:25], v38
	ds_read_b128 v[26:29], v38 offset:64
	ds_read_b128 v[34:37], v38 offset:128
	ds_read_b128 v[38:41], v38 offset:192
	v_bfe_u32 v45, v52, 4, 2
	v_add_u32_e32 v0, s4, v0
	v_lshlrev_b64 v[50:51], 8, v[50:51]
	v_or_b32_e32 v86, v0, v58
	v_or_b32_e32 v106, 15, v0
	v_lshlrev_b32_e32 v0, 2, v45
	v_cmp_ne_u32_e64 s[40:41], 1, v45
	v_cmp_eq_u32_e64 s[42:43], 2, v45
	v_lshlrev_b32_e32 v111, 3, v45
	v_lshlrev_b32_e32 v45, 4, v58
	v_lshl_add_u64 v[90:91], s[0:1], 0, v[50:51]
	v_or_b32_e32 v88, v88, v45
	v_or_b32_e32 v90, v90, v45
	v_or_b32_e32 v45, s17, v87
	v_lshlrev_b32_e32 v45, 8, v45
	s_mov_b64 s[0:1], 0x17214000
	v_or3_b32 v42, v42, v45, v44
	v_or3_b32 v46, v46, v45, v48
	v_lshl_add_u64 v[94:95], v[42:43], 0, s[0:1]
	v_mov_b32_e32 v42, 0
	v_lshl_add_u64 v[92:93], v[46:47], 0, s[0:1]
	v_mov_b32_e32 v43, v42
	v_mov_b32_e32 v44, v42
	v_mov_b32_e32 v45, v42
	v_mov_b32_e32 v58, v42
	v_mov_b32_e32 v59, v42
	v_mov_b32_e32 v60, v42
	v_mov_b32_e32 v61, v42
	v_mov_b32_e32 v54, v42
	v_mov_b32_e32 v55, v42
	v_mov_b32_e32 v56, v42
	v_mov_b32_e32 v57, v42
	v_mov_b32_e32 v50, v42
	v_mov_b32_e32 v51, v42
	v_mov_b32_e32 v52, v42
	v_mov_b32_e32 v53, v42
	v_mov_b32_e32 v70, v42
	v_mov_b32_e32 v71, v42
	v_mov_b32_e32 v72, v42
	v_mov_b32_e32 v73, v42
	v_mov_b32_e32 v66, v42
	v_mov_b32_e32 v67, v42
	v_mov_b32_e32 v68, v42
	v_mov_b32_e32 v69, v42
	v_mov_b32_e32 v62, v42
	v_mov_b32_e32 v63, v42
	v_mov_b32_e32 v64, v42
	v_mov_b32_e32 v65, v42
	v_mov_b32_e32 v46, v42
	v_mov_b32_e32 v47, v42
	v_mov_b32_e32 v48, v42
	v_mov_b32_e32 v49, v42
	s_branch .LBB0_124
